# GEMM K-loops: the four LDS read address VALU adds per iteration hoisted to per-unit persistent registers (on top of SGPR-base DMA)
# speedup vs baseline: 1.0081x; 1.0018x over previous
.Lsp_205:
	v_add_u32_e32 v216, 0x10000, v227
	v_add_u32_e32 v217, 0x14000, v227
	v_add_u32_e32 v218, 0x18000, v227
	v_add_u32_e32 v219, 0x1c000, v227
.LBB0_205:
	s_add_u32 s16, s42, 0xfff80080
	s_addc_u32 s17, s43, -1
	s_add_i32 s89, 0, 0x10000
	s_cmp_eq_u32 s88, 28
	s_cselect_b32 s45, s27, s17
	s_cselect_b32 s44, s73, s16
	s_cselect_b32 s29, s23, s78
	s_cselect_b32 s28, s74, s77
	s_add_i32 s91, 0, 0x14000
	ds_read_b128 v[132:135], v216
	ds_read_b128 v[136:139], v216 offset:1024
	ds_read_b128 v[140:143], v216 offset:2048
	ds_read_b128 v[144:147], v216 offset:3072
	ds_read_b128 v[148:151], v217
	ds_read_b128 v[152:155], v217 offset:1024
	ds_read_b128 v[166:169], v217 offset:2048
	ds_read_b128 v[170:173], v217 offset:3072
	s_add_i32 m0, s31, 0xc000
	ds_read_b128 v[184:187], v229
	ds_read_b128 v[188:191], v229 offset:1024
	ds_read_b128 v[192:195], v229 offset:2048
	ds_read_b128 v[196:199], v229 offset:3072
	ds_read_b128 v[200:203], v229 offset:4096
	ds_read_b128 v[204:207], v229 offset:5120
	ds_read_b128 v[208:211], v229 offset:6144
	ds_read_b128 v[212:215], v229 offset:7168
	global_load_lds_dwordx4 v162, s[42:43]
	s_add_i32 m0, s31, 0xe000
	s_nop 0
	global_load_lds_dwordx4 v164, s[42:43]
	s_waitcnt vmcnt(8)
	s_waitcnt lgkmcnt(0)

	s_barrier
	v_mfma_f32_16x16x32_bf16 v[128:131], v[132:135], v[184:187], v[128:131]
	v_mfma_f32_16x16x32_bf16 v[124:127], v[140:143], v[184:187], v[124:127]
	v_mfma_f32_16x16x32_bf16 v[112:115], v[132:135], v[192:195], v[112:115]
	v_mfma_f32_16x16x32_bf16 v[108:111], v[140:143], v[192:195], v[108:111]
	v_mfma_f32_16x16x32_bf16 v[96:99], v[132:135], v[200:203], v[96:99]
	v_mfma_f32_16x16x32_bf16 v[92:95], v[140:143], v[200:203], v[92:95]
	v_mfma_f32_16x16x32_bf16 v[80:83], v[132:135], v[208:211], v[80:83]
	v_mfma_f32_16x16x32_bf16 v[76:79], v[140:143], v[208:211], v[76:79]
	v_mfma_f32_16x16x32_bf16 v[128:131], v[136:139], v[188:191], v[128:131]
	v_mfma_f32_16x16x32_bf16 v[124:127], v[144:147], v[188:191], v[124:127]
	v_mfma_f32_16x16x32_bf16 v[112:115], v[136:139], v[196:199], v[112:115]
	v_mfma_f32_16x16x32_bf16 v[108:111], v[144:147], v[196:199], v[108:111]
	v_mfma_f32_16x16x32_bf16 v[96:99], v[136:139], v[204:207], v[96:99]
	v_mfma_f32_16x16x32_bf16 v[92:95], v[144:147], v[204:207], v[92:95]
	v_mfma_f32_16x16x32_bf16 v[80:83], v[136:139], v[212:215], v[80:83]
	v_mfma_f32_16x16x32_bf16 v[76:79], v[144:147], v[212:215], v[76:79]
	v_mfma_f32_16x16x32_bf16 v[120:123], v[148:151], v[184:187], v[120:123]
	v_mfma_f32_16x16x32_bf16 v[116:119], v[166:169], v[184:187], v[116:119]
	v_mfma_f32_16x16x32_bf16 v[104:107], v[148:151], v[192:195], v[104:107]
	v_mfma_f32_16x16x32_bf16 v[100:103], v[166:169], v[192:195], v[100:103]
	v_mfma_f32_16x16x32_bf16 v[88:91], v[148:151], v[200:203], v[88:91]
	v_mfma_f32_16x16x32_bf16 v[84:87], v[166:169], v[200:203], v[84:87]
	v_mfma_f32_16x16x32_bf16 v[72:75], v[148:151], v[208:211], v[72:75]
	v_mfma_f32_16x16x32_bf16 v[68:71], v[166:169], v[208:211], v[68:71]
	v_mfma_f32_16x16x32_bf16 v[120:123], v[152:155], v[188:191], v[120:123]
	v_mfma_f32_16x16x32_bf16 v[116:119], v[170:173], v[188:191], v[116:119]
	v_mfma_f32_16x16x32_bf16 v[104:107], v[152:155], v[196:199], v[104:107]
	v_mfma_f32_16x16x32_bf16 v[100:103], v[170:173], v[196:199], v[100:103]
	v_mfma_f32_16x16x32_bf16 v[88:91], v[152:155], v[204:207], v[88:91]
	v_mfma_f32_16x16x32_bf16 v[84:87], v[170:173], v[204:207], v[84:87]
	v_mfma_f32_16x16x32_bf16 v[72:75], v[152:155], v[212:215], v[72:75]
	v_mfma_f32_16x16x32_bf16 v[68:71], v[170:173], v[212:215], v[68:71]
	s_barrier

	s_add_i32 s16, s89, s3
	s_mov_b32 m0, s16
	ds_read_b128 v[184:187], v229 offset:16384
	ds_read_b128 v[188:191], v229 offset:17408
	ds_read_b128 v[192:195], v229 offset:18432
	ds_read_b128 v[196:199], v229 offset:19456
	ds_read_b128 v[200:203], v229 offset:20480
	ds_read_b128 v[204:207], v229 offset:21504
	ds_read_b128 v[208:211], v229 offset:22528
	ds_read_b128 v[212:215], v229 offset:23552
	global_load_lds_dwordx4 v2, s[28:29]
	s_add_i32 m0, s16, 0x2000
	s_add_u32 s16, s28, 0x80000
	s_addc_u32 s17, s29, 0
	s_add_i32 s89, s91, s3
	global_load_lds_dwordx4 v156, s[28:29]
	s_mov_b32 m0, s89
	s_nop 0
	global_load_lds_dwordx4 v2, s[16:17]
	s_add_i32 m0, s89, 0x2000
	s_nop 0
	global_load_lds_dwordx4 v156, s[16:17]
	s_mov_b32 m0, s31
	s_nop 0
	global_load_lds_dwordx4 v160, s[44:45]
	s_mov_b32 m0, s33
	s_nop 0
	global_load_lds_dwordx4 v158, s[44:45]
	s_waitcnt vmcnt(8)
	s_waitcnt lgkmcnt(0)

	s_barrier
	v_mfma_f32_16x16x32_bf16 v[64:67], v[132:135], v[184:187], v[64:67]
	v_mfma_f32_16x16x32_bf16 v[60:63], v[140:143], v[184:187], v[60:63]
	v_mfma_f32_16x16x32_bf16 v[48:51], v[132:135], v[192:195], v[48:51]
	v_mfma_f32_16x16x32_bf16 v[44:47], v[140:143], v[192:195], v[44:47]
	v_mfma_f32_16x16x32_bf16 v[32:35], v[132:135], v[200:203], v[32:35]
	v_mfma_f32_16x16x32_bf16 v[28:31], v[140:143], v[200:203], v[28:31]
	v_mfma_f32_16x16x32_bf16 v[16:19], v[132:135], v[208:211], v[16:19]
	v_mfma_f32_16x16x32_bf16 v[12:15], v[140:143], v[208:211], v[12:15]
	v_mfma_f32_16x16x32_bf16 v[64:67], v[136:139], v[188:191], v[64:67]
	v_mfma_f32_16x16x32_bf16 v[60:63], v[144:147], v[188:191], v[60:63]
	v_mfma_f32_16x16x32_bf16 v[48:51], v[136:139], v[196:199], v[48:51]
	v_mfma_f32_16x16x32_bf16 v[44:47], v[144:147], v[196:199], v[44:47]
	v_mfma_f32_16x16x32_bf16 v[32:35], v[136:139], v[204:207], v[32:35]
	v_mfma_f32_16x16x32_bf16 v[28:31], v[144:147], v[204:207], v[28:31]
	v_mfma_f32_16x16x32_bf16 v[16:19], v[136:139], v[212:215], v[16:19]
	v_mfma_f32_16x16x32_bf16 v[12:15], v[144:147], v[212:215], v[12:15]
	v_mfma_f32_16x16x32_bf16 v[56:59], v[148:151], v[184:187], v[56:59]
	v_mfma_f32_16x16x32_bf16 v[52:55], v[166:169], v[184:187], v[52:55]
	v_mfma_f32_16x16x32_bf16 v[40:43], v[148:151], v[192:195], v[40:43]
	v_mfma_f32_16x16x32_bf16 v[36:39], v[166:169], v[192:195], v[36:39]
	v_mfma_f32_16x16x32_bf16 v[24:27], v[148:151], v[200:203], v[24:27]
	v_mfma_f32_16x16x32_bf16 v[20:23], v[166:169], v[200:203], v[20:23]
	v_mfma_f32_16x16x32_bf16 v[8:11], v[148:151], v[208:211], v[8:11]
	v_mfma_f32_16x16x32_bf16 v[4:7], v[166:169], v[208:211], v[4:7]
	v_mfma_f32_16x16x32_bf16 v[56:59], v[152:155], v[188:191], v[56:59]
	v_mfma_f32_16x16x32_bf16 v[52:55], v[170:173], v[188:191], v[52:55]
	v_mfma_f32_16x16x32_bf16 v[40:43], v[152:155], v[196:199], v[40:43]
	v_mfma_f32_16x16x32_bf16 v[36:39], v[170:173], v[196:199], v[36:39]
	v_mfma_f32_16x16x32_bf16 v[24:27], v[152:155], v[204:207], v[24:27]
	v_mfma_f32_16x16x32_bf16 v[20:23], v[170:173], v[204:207], v[20:23]
	v_mfma_f32_16x16x32_bf16 v[8:11], v[152:155], v[212:215], v[8:11]
	v_mfma_f32_16x16x32_bf16 v[4:7], v[170:173], v[212:215], v[4:7]
	s_barrier

	s_add_i32 s89, 0, 0x18000
	s_add_i32 s91, 0, 0x1c000
	ds_read_b128 v[132:135], v218
	ds_read_b128 v[136:139], v218 offset:1024
	ds_read_b128 v[140:143], v218 offset:2048
	ds_read_b128 v[144:147], v218 offset:3072
	ds_read_b128 v[148:151], v219
	ds_read_b128 v[152:155], v219 offset:1024
	ds_read_b128 v[166:169], v219 offset:2048
	ds_read_b128 v[170:173], v219 offset:3072
	s_add_u32 s16, s44, 0x80000
	s_addc_u32 s17, s45, 0
	s_mov_b32 m0, s46
	ds_read_b128 v[184:187], v229 offset:32768
	ds_read_b128 v[188:191], v229 offset:33792
	ds_read_b128 v[192:195], v229 offset:34816
	ds_read_b128 v[196:199], v229 offset:35840
	ds_read_b128 v[200:203], v229 offset:36864
	ds_read_b128 v[204:207], v229 offset:37888
	ds_read_b128 v[208:211], v229 offset:38912
	ds_read_b128 v[212:215], v229 offset:39936
	global_load_lds_dwordx4 v160, s[16:17]
	s_mov_b32 m0, s47
	s_nop 0
	global_load_lds_dwordx4 v158, s[16:17]
	s_waitcnt vmcnt(8)
	s_waitcnt lgkmcnt(0)

	s_barrier
	v_mfma_f32_16x16x32_bf16 v[128:131], v[132:135], v[184:187], v[128:131]
	v_mfma_f32_16x16x32_bf16 v[124:127], v[140:143], v[184:187], v[124:127]
	v_mfma_f32_16x16x32_bf16 v[112:115], v[132:135], v[192:195], v[112:115]
	v_mfma_f32_16x16x32_bf16 v[108:111], v[140:143], v[192:195], v[108:111]
	v_mfma_f32_16x16x32_bf16 v[96:99], v[132:135], v[200:203], v[96:99]
	v_mfma_f32_16x16x32_bf16 v[92:95], v[140:143], v[200:203], v[92:95]
	v_mfma_f32_16x16x32_bf16 v[80:83], v[132:135], v[208:211], v[80:83]
	v_mfma_f32_16x16x32_bf16 v[76:79], v[140:143], v[208:211], v[76:79]
	v_mfma_f32_16x16x32_bf16 v[128:131], v[136:139], v[188:191], v[128:131]
	v_mfma_f32_16x16x32_bf16 v[124:127], v[144:147], v[188:191], v[124:127]
	v_mfma_f32_16x16x32_bf16 v[112:115], v[136:139], v[196:199], v[112:115]
	v_mfma_f32_16x16x32_bf16 v[108:111], v[144:147], v[196:199], v[108:111]
	v_mfma_f32_16x16x32_bf16 v[96:99], v[136:139], v[204:207], v[96:99]
	v_mfma_f32_16x16x32_bf16 v[92:95], v[144:147], v[204:207], v[92:95]
	v_mfma_f32_16x16x32_bf16 v[80:83], v[136:139], v[212:215], v[80:83]
	v_mfma_f32_16x16x32_bf16 v[76:79], v[144:147], v[212:215], v[76:79]
	v_mfma_f32_16x16x32_bf16 v[120:123], v[148:151], v[184:187], v[120:123]
	v_mfma_f32_16x16x32_bf16 v[116:119], v[166:169], v[184:187], v[116:119]
	v_mfma_f32_16x16x32_bf16 v[104:107], v[148:151], v[192:195], v[104:107]
	v_mfma_f32_16x16x32_bf16 v[100:103], v[166:169], v[192:195], v[100:103]
	v_mfma_f32_16x16x32_bf16 v[88:91], v[148:151], v[200:203], v[88:91]
	v_mfma_f32_16x16x32_bf16 v[84:87], v[166:169], v[200:203], v[84:87]
	v_mfma_f32_16x16x32_bf16 v[72:75], v[148:151], v[208:211], v[72:75]
	v_mfma_f32_16x16x32_bf16 v[68:71], v[166:169], v[208:211], v[68:71]
	v_mfma_f32_16x16x32_bf16 v[120:123], v[152:155], v[188:191], v[120:123]
	v_mfma_f32_16x16x32_bf16 v[116:119], v[170:173], v[188:191], v[116:119]
	v_mfma_f32_16x16x32_bf16 v[104:107], v[152:155], v[196:199], v[104:107]
	v_mfma_f32_16x16x32_bf16 v[100:103], v[170:173], v[196:199], v[100:103]
	v_mfma_f32_16x16x32_bf16 v[88:91], v[152:155], v[204:207], v[88:91]
	v_mfma_f32_16x16x32_bf16 v[84:87], v[170:173], v[204:207], v[84:87]
	v_mfma_f32_16x16x32_bf16 v[72:75], v[152:155], v[212:215], v[72:75]
	v_mfma_f32_16x16x32_bf16 v[68:71], v[170:173], v[212:215], v[68:71]
	s_barrier

	s_add_i32 s16, s89, s3
	s_mov_b32 m0, s16
	ds_read_b128 v[184:187], v229 offset:49152
	ds_read_b128 v[188:191], v229 offset:50176
	ds_read_b128 v[192:195], v229 offset:51200
	ds_read_b128 v[196:199], v229 offset:52224
	ds_read_b128 v[200:203], v229 offset:53248
	ds_read_b128 v[204:207], v229 offset:54272
	ds_read_b128 v[208:211], v229 offset:55296
	ds_read_b128 v[212:215], v229 offset:56320
	s_add_u32 s100, s28, s24
	s_addc_u32 s101, s29, s25
	global_load_lds_dwordx4 v2, s[100:101]
	s_add_i32 m0, s16, 0x2000
	s_add_u32 s16, s28, 0x80080
	s_addc_u32 s17, s29, 0
	s_add_i32 s28, s91, s3
	global_load_lds_dwordx4 v156, s[100:101]
	s_mov_b32 m0, s28
	s_nop 0
	global_load_lds_dwordx4 v2, s[16:17]
	s_add_i32 m0, s28, 0x2000
	s_nop 0
	global_load_lds_dwordx4 v156, s[16:17]
	s_mov_b32 m0, s48
	s_nop 0
	s_add_u32 s100, s44, s24
	s_addc_u32 s101, s45, s25
	global_load_lds_dwordx4 v160, s[100:101]
	s_mov_b32 m0, s49
	s_nop 0
	global_load_lds_dwordx4 v158, s[100:101]
	s_waitcnt vmcnt(8)
	s_waitcnt lgkmcnt(0)

	s_barrier
	v_mfma_f32_16x16x32_bf16 v[64:67], v[132:135], v[184:187], v[64:67]
	v_mfma_f32_16x16x32_bf16 v[60:63], v[140:143], v[184:187], v[60:63]
	v_mfma_f32_16x16x32_bf16 v[48:51], v[132:135], v[192:195], v[48:51]
	v_mfma_f32_16x16x32_bf16 v[44:47], v[140:143], v[192:195], v[44:47]
	v_mfma_f32_16x16x32_bf16 v[32:35], v[132:135], v[200:203], v[32:35]
	v_mfma_f32_16x16x32_bf16 v[28:31], v[140:143], v[200:203], v[28:31]
	v_mfma_f32_16x16x32_bf16 v[16:19], v[132:135], v[208:211], v[16:19]
	v_mfma_f32_16x16x32_bf16 v[12:15], v[140:143], v[208:211], v[12:15]
	v_mfma_f32_16x16x32_bf16 v[64:67], v[136:139], v[188:191], v[64:67]
	v_mfma_f32_16x16x32_bf16 v[60:63], v[144:147], v[188:191], v[60:63]
	v_mfma_f32_16x16x32_bf16 v[48:51], v[136:139], v[196:199], v[48:51]
	v_mfma_f32_16x16x32_bf16 v[44:47], v[144:147], v[196:199], v[44:47]
	v_mfma_f32_16x16x32_bf16 v[32:35], v[136:139], v[204:207], v[32:35]
	v_mfma_f32_16x16x32_bf16 v[28:31], v[144:147], v[204:207], v[28:31]
	v_mfma_f32_16x16x32_bf16 v[16:19], v[136:139], v[212:215], v[16:19]
	v_mfma_f32_16x16x32_bf16 v[12:15], v[144:147], v[212:215], v[12:15]
	v_mfma_f32_16x16x32_bf16 v[56:59], v[148:151], v[184:187], v[56:59]
	v_mfma_f32_16x16x32_bf16 v[52:55], v[166:169], v[184:187], v[52:55]
	v_mfma_f32_16x16x32_bf16 v[40:43], v[148:151], v[192:195], v[40:43]
	v_mfma_f32_16x16x32_bf16 v[36:39], v[166:169], v[192:195], v[36:39]
	v_mfma_f32_16x16x32_bf16 v[24:27], v[148:151], v[200:203], v[24:27]
	v_mfma_f32_16x16x32_bf16 v[20:23], v[166:169], v[200:203], v[20:23]
	v_mfma_f32_16x16x32_bf16 v[8:11], v[148:151], v[208:211], v[8:11]
	v_mfma_f32_16x16x32_bf16 v[4:7], v[166:169], v[208:211], v[4:7]
	v_mfma_f32_16x16x32_bf16 v[56:59], v[152:155], v[188:191], v[56:59]
	v_mfma_f32_16x16x32_bf16 v[52:55], v[170:173], v[188:191], v[52:55]
	v_mfma_f32_16x16x32_bf16 v[40:43], v[152:155], v[196:199], v[40:43]
	v_mfma_f32_16x16x32_bf16 v[36:39], v[170:173], v[196:199], v[36:39]
	v_mfma_f32_16x16x32_bf16 v[24:27], v[152:155], v[204:207], v[24:27]
	v_mfma_f32_16x16x32_bf16 v[20:23], v[170:173], v[204:207], v[20:23]
	v_mfma_f32_16x16x32_bf16 v[8:11], v[152:155], v[212:215], v[8:11]
	v_mfma_f32_16x16x32_bf16 v[4:7], v[170:173], v[212:215], v[4:7]
	s_barrier

	s_add_i32 s88, s88, 2
	s_add_u32 s42, s42, 0x100
	s_addc_u32 s43, s43, 0
	s_add_u32 s77, s77, 0x100
	s_addc_u32 s78, s78, 0
	s_cmp_gt_u32 s88, 29
	s_cbranch_scc0 .LBB0_205
	s_setprio 0
	v_mov_b32_e32 v176, 0xc2000000

.Lsp_366:
	v_add_u32_e32 v174, 0x10000, v244
	v_add_u32_e32 v175, 0x14000, v244
	v_add_u32_e32 v182, 0x18000, v244
	v_add_u32_e32 v183, 0x1c000, v244
.LBB0_366:
	s_add_u32 s48, s50, 0x100
	s_addc_u32 s49, s51, 0
	s_add_i32 s16, 0, 0x10000
	s_cmpk_eq_i32 s22, 0x54
	s_cselect_b32 vcc_hi, s19, s49
	s_cselect_b32 vcc_lo, s18, s48
	s_cselect_b32 s29, s27, s33
	s_cselect_b32 s28, s26, s31
	s_add_i32 s23, 0, 0x14000
	ds_read_b128 v[132:135], v174
	ds_read_b128 v[136:139], v174 offset:1024
	ds_read_b128 v[140:143], v174 offset:2048
	ds_read_b128 v[144:147], v174 offset:3072
	ds_read_b128 v[148:151], v175
	ds_read_b128 v[152:155], v175 offset:1024
	ds_read_b128 v[156:159], v175 offset:2048
	ds_read_b128 v[160:163], v175 offset:3072
	s_add_i32 m0, s74, 0xc000
	ds_read_b128 v[164:167], v246
	ds_read_b128 v[188:191], v246 offset:1024
	ds_read_b128 v[192:195], v246 offset:2048
	ds_read_b128 v[196:199], v246 offset:3072
	ds_read_b128 v[200:203], v246 offset:4096
	ds_read_b128 v[204:207], v246 offset:5120
	ds_read_b128 v[208:211], v246 offset:6144
	ds_read_b128 v[212:215], v246 offset:7168
	global_load_lds_dwordx4 v184, s[50:51]
	s_add_i32 m0, s74, 0xe000
	s_nop 0
	global_load_lds_dwordx4 v186, s[50:51]
	s_waitcnt vmcnt(8)
	s_waitcnt lgkmcnt(0)

	s_barrier
	v_mfma_f32_16x16x32_bf16 v[128:131], v[132:135], v[164:167], v[128:131]
	v_mfma_f32_16x16x32_bf16 v[124:127], v[140:143], v[164:167], v[124:127]
	v_mfma_f32_16x16x32_bf16 v[112:115], v[132:135], v[192:195], v[112:115]
	v_mfma_f32_16x16x32_bf16 v[108:111], v[140:143], v[192:195], v[108:111]
	v_mfma_f32_16x16x32_bf16 v[96:99], v[132:135], v[200:203], v[96:99]
	v_mfma_f32_16x16x32_bf16 v[92:95], v[140:143], v[200:203], v[92:95]
	v_mfma_f32_16x16x32_bf16 v[80:83], v[132:135], v[208:211], v[80:83]
	v_mfma_f32_16x16x32_bf16 v[76:79], v[140:143], v[208:211], v[76:79]
	v_mfma_f32_16x16x32_bf16 v[128:131], v[136:139], v[188:191], v[128:131]
	v_mfma_f32_16x16x32_bf16 v[124:127], v[144:147], v[188:191], v[124:127]
	v_mfma_f32_16x16x32_bf16 v[112:115], v[136:139], v[196:199], v[112:115]
	v_mfma_f32_16x16x32_bf16 v[108:111], v[144:147], v[196:199], v[108:111]
	v_mfma_f32_16x16x32_bf16 v[96:99], v[136:139], v[204:207], v[96:99]
	v_mfma_f32_16x16x32_bf16 v[92:95], v[144:147], v[204:207], v[92:95]
	v_mfma_f32_16x16x32_bf16 v[80:83], v[136:139], v[212:215], v[80:83]
	v_mfma_f32_16x16x32_bf16 v[76:79], v[144:147], v[212:215], v[76:79]
	v_mfma_f32_16x16x32_bf16 v[120:123], v[148:151], v[164:167], v[120:123]
	v_mfma_f32_16x16x32_bf16 v[116:119], v[156:159], v[164:167], v[116:119]
	v_mfma_f32_16x16x32_bf16 v[104:107], v[148:151], v[192:195], v[104:107]
	v_mfma_f32_16x16x32_bf16 v[100:103], v[156:159], v[192:195], v[100:103]
	v_mfma_f32_16x16x32_bf16 v[88:91], v[148:151], v[200:203], v[88:91]
	v_mfma_f32_16x16x32_bf16 v[84:87], v[156:159], v[200:203], v[84:87]
	v_mfma_f32_16x16x32_bf16 v[72:75], v[148:151], v[208:211], v[72:75]
	v_mfma_f32_16x16x32_bf16 v[68:71], v[156:159], v[208:211], v[68:71]
	v_mfma_f32_16x16x32_bf16 v[120:123], v[152:155], v[188:191], v[120:123]
	v_mfma_f32_16x16x32_bf16 v[116:119], v[160:163], v[188:191], v[116:119]
	v_mfma_f32_16x16x32_bf16 v[104:107], v[152:155], v[196:199], v[104:107]
	v_mfma_f32_16x16x32_bf16 v[100:103], v[160:163], v[196:199], v[100:103]
	v_mfma_f32_16x16x32_bf16 v[88:91], v[152:155], v[204:207], v[88:91]
	v_mfma_f32_16x16x32_bf16 v[84:87], v[160:163], v[204:207], v[84:87]
	v_mfma_f32_16x16x32_bf16 v[72:75], v[152:155], v[212:215], v[72:75]
	v_mfma_f32_16x16x32_bf16 v[68:71], v[160:163], v[212:215], v[68:71]
	s_barrier

	s_add_i32 s16, s16, s73
	s_mov_b32 m0, s16
	ds_read_b128 v[164:167], v246 offset:16384
	ds_read_b128 v[188:191], v246 offset:17408
	ds_read_b128 v[192:195], v246 offset:18432
	ds_read_b128 v[196:199], v246 offset:19456
	ds_read_b128 v[200:203], v246 offset:20480
	ds_read_b128 v[204:207], v246 offset:21504
	ds_read_b128 v[208:211], v246 offset:22528
	ds_read_b128 v[212:215], v246 offset:23552
	global_load_lds_dwordx4 v2, s[28:29]
	s_add_i32 m0, s16, 0x2000
	s_add_u32 s16, s28, 0x58000
	s_addc_u32 s17, s29, 0
	s_add_i32 s23, s23, s73
	global_load_lds_dwordx4 v168, s[28:29]
	s_mov_b32 m0, s23
	s_nop 0
	global_load_lds_dwordx4 v2, s[16:17]
	s_add_i32 m0, s23, 0x2000
	s_nop 0
	global_load_lds_dwordx4 v168, s[16:17]
	s_mov_b32 m0, s74
	s_nop 0
	global_load_lds_dwordx4 v172, vcc
	s_mov_b32 m0, s77
	s_nop 0
	global_load_lds_dwordx4 v170, vcc
	s_waitcnt vmcnt(8)
	s_waitcnt lgkmcnt(0)

	s_barrier
	v_mfma_f32_16x16x32_bf16 v[64:67], v[132:135], v[164:167], v[64:67]
	v_mfma_f32_16x16x32_bf16 v[60:63], v[140:143], v[164:167], v[60:63]
	v_mfma_f32_16x16x32_bf16 v[48:51], v[132:135], v[192:195], v[48:51]
	v_mfma_f32_16x16x32_bf16 v[44:47], v[140:143], v[192:195], v[44:47]
	v_mfma_f32_16x16x32_bf16 v[32:35], v[132:135], v[200:203], v[32:35]
	v_mfma_f32_16x16x32_bf16 v[28:31], v[140:143], v[200:203], v[28:31]
	v_mfma_f32_16x16x32_bf16 v[16:19], v[132:135], v[208:211], v[16:19]
	v_mfma_f32_16x16x32_bf16 v[12:15], v[140:143], v[208:211], v[12:15]
	v_mfma_f32_16x16x32_bf16 v[64:67], v[136:139], v[188:191], v[64:67]
	v_mfma_f32_16x16x32_bf16 v[60:63], v[144:147], v[188:191], v[60:63]
	v_mfma_f32_16x16x32_bf16 v[48:51], v[136:139], v[196:199], v[48:51]
	v_mfma_f32_16x16x32_bf16 v[44:47], v[144:147], v[196:199], v[44:47]
	v_mfma_f32_16x16x32_bf16 v[32:35], v[136:139], v[204:207], v[32:35]
	v_mfma_f32_16x16x32_bf16 v[28:31], v[144:147], v[204:207], v[28:31]
	v_mfma_f32_16x16x32_bf16 v[16:19], v[136:139], v[212:215], v[16:19]
	v_mfma_f32_16x16x32_bf16 v[12:15], v[144:147], v[212:215], v[12:15]
	v_mfma_f32_16x16x32_bf16 v[56:59], v[148:151], v[164:167], v[56:59]
	v_mfma_f32_16x16x32_bf16 v[52:55], v[156:159], v[164:167], v[52:55]
	v_mfma_f32_16x16x32_bf16 v[40:43], v[148:151], v[192:195], v[40:43]
	v_mfma_f32_16x16x32_bf16 v[36:39], v[156:159], v[192:195], v[36:39]
	v_mfma_f32_16x16x32_bf16 v[24:27], v[148:151], v[200:203], v[24:27]
	v_mfma_f32_16x16x32_bf16 v[20:23], v[156:159], v[200:203], v[20:23]
	v_mfma_f32_16x16x32_bf16 v[8:11], v[148:151], v[208:211], v[8:11]
	v_mfma_f32_16x16x32_bf16 v[4:7], v[156:159], v[208:211], v[4:7]
	v_mfma_f32_16x16x32_bf16 v[56:59], v[152:155], v[188:191], v[56:59]
	v_mfma_f32_16x16x32_bf16 v[52:55], v[160:163], v[188:191], v[52:55]
	v_mfma_f32_16x16x32_bf16 v[40:43], v[152:155], v[196:199], v[40:43]
	v_mfma_f32_16x16x32_bf16 v[36:39], v[160:163], v[196:199], v[36:39]
	v_mfma_f32_16x16x32_bf16 v[24:27], v[152:155], v[204:207], v[24:27]
	v_mfma_f32_16x16x32_bf16 v[20:23], v[160:163], v[204:207], v[20:23]
	v_mfma_f32_16x16x32_bf16 v[8:11], v[152:155], v[212:215], v[8:11]
	v_mfma_f32_16x16x32_bf16 v[4:7], v[160:163], v[212:215], v[4:7]
	s_barrier

	s_add_i32 s23, 0, 0x18000
	s_add_i32 s50, 0, 0x1c000
	ds_read_b128 v[132:135], v182
	ds_read_b128 v[136:139], v182 offset:1024
	ds_read_b128 v[140:143], v182 offset:2048
	ds_read_b128 v[144:147], v182 offset:3072
	ds_read_b128 v[148:151], v183
	ds_read_b128 v[152:155], v183 offset:1024
	ds_read_b128 v[156:159], v183 offset:2048
	ds_read_b128 v[160:163], v183 offset:3072
	s_add_u32 s16, vcc_lo, 0x160000
	s_addc_u32 s17, vcc_hi, 0
	s_mov_b32 m0, s72
	ds_read_b128 v[164:167], v246 offset:32768
	ds_read_b128 v[188:191], v246 offset:33792
	ds_read_b128 v[192:195], v246 offset:34816
	ds_read_b128 v[196:199], v246 offset:35840
	ds_read_b128 v[200:203], v246 offset:36864
	ds_read_b128 v[204:207], v246 offset:37888
	ds_read_b128 v[208:211], v246 offset:38912
	ds_read_b128 v[212:215], v246 offset:39936
	global_load_lds_dwordx4 v172, s[16:17]
	s_mov_b32 m0, s78
	s_nop 0
	global_load_lds_dwordx4 v170, s[16:17]
	s_waitcnt vmcnt(8)
	s_waitcnt lgkmcnt(0)

	s_barrier
	v_mfma_f32_16x16x32_bf16 v[128:131], v[132:135], v[164:167], v[128:131]
	v_mfma_f32_16x16x32_bf16 v[124:127], v[140:143], v[164:167], v[124:127]
	v_mfma_f32_16x16x32_bf16 v[112:115], v[132:135], v[192:195], v[112:115]
	v_mfma_f32_16x16x32_bf16 v[108:111], v[140:143], v[192:195], v[108:111]
	v_mfma_f32_16x16x32_bf16 v[96:99], v[132:135], v[200:203], v[96:99]
	v_mfma_f32_16x16x32_bf16 v[92:95], v[140:143], v[200:203], v[92:95]
	v_mfma_f32_16x16x32_bf16 v[80:83], v[132:135], v[208:211], v[80:83]
	v_mfma_f32_16x16x32_bf16 v[76:79], v[140:143], v[208:211], v[76:79]
	v_mfma_f32_16x16x32_bf16 v[128:131], v[136:139], v[188:191], v[128:131]
	v_mfma_f32_16x16x32_bf16 v[124:127], v[144:147], v[188:191], v[124:127]
	v_mfma_f32_16x16x32_bf16 v[112:115], v[136:139], v[196:199], v[112:115]
	v_mfma_f32_16x16x32_bf16 v[108:111], v[144:147], v[196:199], v[108:111]
	v_mfma_f32_16x16x32_bf16 v[96:99], v[136:139], v[204:207], v[96:99]
	v_mfma_f32_16x16x32_bf16 v[92:95], v[144:147], v[204:207], v[92:95]
	v_mfma_f32_16x16x32_bf16 v[80:83], v[136:139], v[212:215], v[80:83]
	v_mfma_f32_16x16x32_bf16 v[76:79], v[144:147], v[212:215], v[76:79]
	v_mfma_f32_16x16x32_bf16 v[120:123], v[148:151], v[164:167], v[120:123]
	v_mfma_f32_16x16x32_bf16 v[116:119], v[156:159], v[164:167], v[116:119]
	v_mfma_f32_16x16x32_bf16 v[104:107], v[148:151], v[192:195], v[104:107]
	v_mfma_f32_16x16x32_bf16 v[100:103], v[156:159], v[192:195], v[100:103]
	v_mfma_f32_16x16x32_bf16 v[88:91], v[148:151], v[200:203], v[88:91]
	v_mfma_f32_16x16x32_bf16 v[84:87], v[156:159], v[200:203], v[84:87]
	v_mfma_f32_16x16x32_bf16 v[72:75], v[148:151], v[208:211], v[72:75]
	v_mfma_f32_16x16x32_bf16 v[68:71], v[156:159], v[208:211], v[68:71]
	v_mfma_f32_16x16x32_bf16 v[120:123], v[152:155], v[188:191], v[120:123]
	v_mfma_f32_16x16x32_bf16 v[116:119], v[160:163], v[188:191], v[116:119]
	v_mfma_f32_16x16x32_bf16 v[104:107], v[152:155], v[196:199], v[104:107]
	v_mfma_f32_16x16x32_bf16 v[100:103], v[160:163], v[196:199], v[100:103]
	v_mfma_f32_16x16x32_bf16 v[88:91], v[152:155], v[204:207], v[88:91]
	v_mfma_f32_16x16x32_bf16 v[84:87], v[160:163], v[204:207], v[84:87]
	v_mfma_f32_16x16x32_bf16 v[72:75], v[152:155], v[212:215], v[72:75]
	v_mfma_f32_16x16x32_bf16 v[68:71], v[160:163], v[212:215], v[68:71]
	s_barrier

	s_add_i32 s16, s23, s73
	s_mov_b32 m0, s16
	ds_read_b128 v[164:167], v246 offset:49152
	ds_read_b128 v[188:191], v246 offset:50176
	ds_read_b128 v[192:195], v246 offset:51200
	ds_read_b128 v[196:199], v246 offset:52224
	ds_read_b128 v[200:203], v246 offset:53248
	ds_read_b128 v[204:207], v246 offset:54272
	ds_read_b128 v[208:211], v246 offset:55296
	ds_read_b128 v[212:215], v246 offset:56320
	s_add_u32 s100, s28, s24
	s_addc_u32 s101, s29, s25
	global_load_lds_dwordx4 v2, s[100:101]
	s_add_i32 m0, s16, 0x2000
	s_add_u32 s16, s28, 0x58080
	s_addc_u32 s17, s29, 0
	s_add_i32 s23, s50, s73
	global_load_lds_dwordx4 v168, s[100:101]
	s_mov_b32 m0, s23
	s_nop 0
	global_load_lds_dwordx4 v2, s[16:17]
	s_add_i32 m0, s23, 0x2000
	s_nop 0
	global_load_lds_dwordx4 v168, s[16:17]
	s_mov_b32 m0, s36
	s_nop 0
	s_add_u32 s100, vcc_lo, s24
	s_addc_u32 s101, vcc_hi, s25
	global_load_lds_dwordx4 v172, s[100:101]
	s_mov_b32 m0, s37
	s_nop 0
	global_load_lds_dwordx4 v170, s[100:101]
	s_waitcnt vmcnt(8)
	s_waitcnt lgkmcnt(0)

	s_barrier
	v_mfma_f32_16x16x32_bf16 v[64:67], v[132:135], v[164:167], v[64:67]
	v_mfma_f32_16x16x32_bf16 v[60:63], v[140:143], v[164:167], v[60:63]
	v_mfma_f32_16x16x32_bf16 v[48:51], v[132:135], v[192:195], v[48:51]
	v_mfma_f32_16x16x32_bf16 v[44:47], v[140:143], v[192:195], v[44:47]
	v_mfma_f32_16x16x32_bf16 v[32:35], v[132:135], v[200:203], v[32:35]
	v_mfma_f32_16x16x32_bf16 v[28:31], v[140:143], v[200:203], v[28:31]
	v_mfma_f32_16x16x32_bf16 v[16:19], v[132:135], v[208:211], v[16:19]
	v_mfma_f32_16x16x32_bf16 v[12:15], v[140:143], v[208:211], v[12:15]
	v_mfma_f32_16x16x32_bf16 v[64:67], v[136:139], v[188:191], v[64:67]
	v_mfma_f32_16x16x32_bf16 v[60:63], v[144:147], v[188:191], v[60:63]
	v_mfma_f32_16x16x32_bf16 v[48:51], v[136:139], v[196:199], v[48:51]
	v_mfma_f32_16x16x32_bf16 v[44:47], v[144:147], v[196:199], v[44:47]
	v_mfma_f32_16x16x32_bf16 v[32:35], v[136:139], v[204:207], v[32:35]
	v_mfma_f32_16x16x32_bf16 v[28:31], v[144:147], v[204:207], v[28:31]
	v_mfma_f32_16x16x32_bf16 v[16:19], v[136:139], v[212:215], v[16:19]
	v_mfma_f32_16x16x32_bf16 v[12:15], v[144:147], v[212:215], v[12:15]
	v_mfma_f32_16x16x32_bf16 v[56:59], v[148:151], v[164:167], v[56:59]
	v_mfma_f32_16x16x32_bf16 v[52:55], v[156:159], v[164:167], v[52:55]
	v_mfma_f32_16x16x32_bf16 v[40:43], v[148:151], v[192:195], v[40:43]
	v_mfma_f32_16x16x32_bf16 v[36:39], v[156:159], v[192:195], v[36:39]
	v_mfma_f32_16x16x32_bf16 v[24:27], v[148:151], v[200:203], v[24:27]
	v_mfma_f32_16x16x32_bf16 v[20:23], v[156:159], v[200:203], v[20:23]
	v_mfma_f32_16x16x32_bf16 v[8:11], v[148:151], v[208:211], v[8:11]
	v_mfma_f32_16x16x32_bf16 v[4:7], v[156:159], v[208:211], v[4:7]
	v_mfma_f32_16x16x32_bf16 v[56:59], v[152:155], v[188:191], v[56:59]
	v_mfma_f32_16x16x32_bf16 v[52:55], v[160:163], v[188:191], v[52:55]
	v_mfma_f32_16x16x32_bf16 v[40:43], v[152:155], v[196:199], v[40:43]
	v_mfma_f32_16x16x32_bf16 v[36:39], v[160:163], v[196:199], v[36:39]
	v_mfma_f32_16x16x32_bf16 v[24:27], v[152:155], v[204:207], v[24:27]
	v_mfma_f32_16x16x32_bf16 v[20:23], v[160:163], v[204:207], v[20:23]
	v_mfma_f32_16x16x32_bf16 v[8:11], v[152:155], v[212:215], v[8:11]
	v_mfma_f32_16x16x32_bf16 v[4:7], v[160:163], v[212:215], v[4:7]
	s_barrier

	s_add_i32 s22, s22, 2
	s_add_u32 s31, s31, 0x100
	s_addc_u32 s33, s33, 0
	s_cmpk_gt_u32 s22, 0x55
	s_mov_b64 s[50:51], s[48:49]
	s_cbranch_scc0 .LBB0_366
	s_setprio 0
	v_readlane_b32 s16, v252, 12
	v_readlane_b32 s17, v252, 13

.Lsp_446:
	v_add_u32_e32 v173, 0x10000, v219
	v_add_u32_e32 v174, 0x14000, v219
	v_add_u32_e32 v175, 0x18000, v219
	v_add_u32_e32 v182, 0x1c000, v219
.LBB0_446:
	s_add_u32 s16, s44, 0xfff80080
	s_addc_u32 s17, s45, -1
	s_add_i32 s94, 0, 0x10000
	s_cmp_eq_u32 vcc_lo, 28
	s_cselect_b32 s47, s37, s17
	s_cselect_b32 s46, s88, s16
	s_cselect_b32 s29, s27, s96
	s_cselect_b32 s28, s89, s91
	s_add_i32 s95, 0, 0x14000
	ds_read_b128 v[132:135], v173
	ds_read_b128 v[136:139], v173 offset:1024
	ds_read_b128 v[140:143], v173 offset:2048
	ds_read_b128 v[144:147], v173 offset:3072
	ds_read_b128 v[148:151], v174
	ds_read_b128 v[164:167], v174 offset:1024
	ds_read_b128 v[168:171], v174 offset:2048
	ds_read_b128 v[184:187], v174 offset:3072
	s_add_i32 m0, s48, 0xc000
	ds_read_b128 v[188:191], v221
	ds_read_b128 v[192:195], v221 offset:1024
	ds_read_b128 v[196:199], v221 offset:2048
	ds_read_b128 v[200:203], v221 offset:3072
	ds_read_b128 v[204:207], v221 offset:4096
	ds_read_b128 v[208:211], v221 offset:5120
	ds_read_b128 v[212:215], v221 offset:6144
	ds_read_b128 v[222:225], v221 offset:7168
	global_load_lds_dwordx4 v160, s[44:45]
	s_add_i32 m0, s48, 0xe000
	s_nop 0
	global_load_lds_dwordx4 v162, s[44:45]
	s_waitcnt vmcnt(8)
	s_waitcnt lgkmcnt(0)

	s_barrier
	v_mfma_f32_16x16x32_bf16 v[128:131], v[132:135], v[188:191], v[128:131]
	v_mfma_f32_16x16x32_bf16 v[124:127], v[140:143], v[188:191], v[124:127]
	v_mfma_f32_16x16x32_bf16 v[112:115], v[132:135], v[196:199], v[112:115]
	v_mfma_f32_16x16x32_bf16 v[108:111], v[140:143], v[196:199], v[108:111]
	v_mfma_f32_16x16x32_bf16 v[96:99], v[132:135], v[204:207], v[96:99]
	v_mfma_f32_16x16x32_bf16 v[92:95], v[140:143], v[204:207], v[92:95]
	v_mfma_f32_16x16x32_bf16 v[80:83], v[132:135], v[212:215], v[80:83]
	v_mfma_f32_16x16x32_bf16 v[76:79], v[140:143], v[212:215], v[76:79]
	v_mfma_f32_16x16x32_bf16 v[128:131], v[136:139], v[192:195], v[128:131]
	v_mfma_f32_16x16x32_bf16 v[124:127], v[144:147], v[192:195], v[124:127]
	v_mfma_f32_16x16x32_bf16 v[112:115], v[136:139], v[200:203], v[112:115]
	v_mfma_f32_16x16x32_bf16 v[108:111], v[144:147], v[200:203], v[108:111]
	v_mfma_f32_16x16x32_bf16 v[96:99], v[136:139], v[208:211], v[96:99]
	v_mfma_f32_16x16x32_bf16 v[92:95], v[144:147], v[208:211], v[92:95]
	v_mfma_f32_16x16x32_bf16 v[80:83], v[136:139], v[222:225], v[80:83]
	v_mfma_f32_16x16x32_bf16 v[76:79], v[144:147], v[222:225], v[76:79]
	v_mfma_f32_16x16x32_bf16 v[120:123], v[148:151], v[188:191], v[120:123]
	v_mfma_f32_16x16x32_bf16 v[116:119], v[168:171], v[188:191], v[116:119]
	v_mfma_f32_16x16x32_bf16 v[104:107], v[148:151], v[196:199], v[104:107]
	v_mfma_f32_16x16x32_bf16 v[100:103], v[168:171], v[196:199], v[100:103]
	v_mfma_f32_16x16x32_bf16 v[88:91], v[148:151], v[204:207], v[88:91]
	v_mfma_f32_16x16x32_bf16 v[84:87], v[168:171], v[204:207], v[84:87]
	v_mfma_f32_16x16x32_bf16 v[72:75], v[148:151], v[212:215], v[72:75]
	v_mfma_f32_16x16x32_bf16 v[68:71], v[168:171], v[212:215], v[68:71]
	v_mfma_f32_16x16x32_bf16 v[120:123], v[164:167], v[192:195], v[120:123]
	v_mfma_f32_16x16x32_bf16 v[116:119], v[184:187], v[192:195], v[116:119]
	v_mfma_f32_16x16x32_bf16 v[104:107], v[164:167], v[200:203], v[104:107]
	v_mfma_f32_16x16x32_bf16 v[100:103], v[184:187], v[200:203], v[100:103]
	v_mfma_f32_16x16x32_bf16 v[88:91], v[164:167], v[208:211], v[88:91]
	v_mfma_f32_16x16x32_bf16 v[84:87], v[184:187], v[208:211], v[84:87]
	v_mfma_f32_16x16x32_bf16 v[72:75], v[164:167], v[222:225], v[72:75]
	v_mfma_f32_16x16x32_bf16 v[68:71], v[184:187], v[222:225], v[68:71]
	s_barrier

	s_add_i32 s16, s94, s33
	s_mov_b32 m0, s16
	ds_read_b128 v[188:191], v221 offset:16384
	ds_read_b128 v[192:195], v221 offset:17408
	ds_read_b128 v[196:199], v221 offset:18432
	ds_read_b128 v[200:203], v221 offset:19456
	ds_read_b128 v[204:207], v221 offset:20480
	ds_read_b128 v[208:211], v221 offset:21504
	ds_read_b128 v[212:215], v221 offset:22528
	ds_read_b128 v[222:225], v221 offset:23552
	global_load_lds_dwordx4 v2, s[28:29]
	s_add_i32 m0, s16, 0x2000
	s_add_u32 s16, s28, 0x80000
	s_addc_u32 s17, s29, 0
	s_add_i32 s94, s95, s33
	global_load_lds_dwordx4 v152, s[28:29]
	s_mov_b32 m0, s94
	s_nop 0
	global_load_lds_dwordx4 v2, s[16:17]
	s_add_i32 m0, s94, 0x2000
	s_nop 0
	global_load_lds_dwordx4 v152, s[16:17]
	s_mov_b32 m0, s48
	s_nop 0
	global_load_lds_dwordx4 v156, s[46:47]
	s_mov_b32 m0, s49
	s_nop 0
	global_load_lds_dwordx4 v154, s[46:47]
	s_waitcnt vmcnt(8)
	s_waitcnt lgkmcnt(0)

	s_barrier
	v_mfma_f32_16x16x32_bf16 v[64:67], v[132:135], v[188:191], v[64:67]
	v_mfma_f32_16x16x32_bf16 v[60:63], v[140:143], v[188:191], v[60:63]
	v_mfma_f32_16x16x32_bf16 v[48:51], v[132:135], v[196:199], v[48:51]
	v_mfma_f32_16x16x32_bf16 v[44:47], v[140:143], v[196:199], v[44:47]
	v_mfma_f32_16x16x32_bf16 v[32:35], v[132:135], v[204:207], v[32:35]
	v_mfma_f32_16x16x32_bf16 v[28:31], v[140:143], v[204:207], v[28:31]
	v_mfma_f32_16x16x32_bf16 v[16:19], v[132:135], v[212:215], v[16:19]
	v_mfma_f32_16x16x32_bf16 v[12:15], v[140:143], v[212:215], v[12:15]
	v_mfma_f32_16x16x32_bf16 v[64:67], v[136:139], v[192:195], v[64:67]
	v_mfma_f32_16x16x32_bf16 v[60:63], v[144:147], v[192:195], v[60:63]
	v_mfma_f32_16x16x32_bf16 v[48:51], v[136:139], v[200:203], v[48:51]
	v_mfma_f32_16x16x32_bf16 v[44:47], v[144:147], v[200:203], v[44:47]
	v_mfma_f32_16x16x32_bf16 v[32:35], v[136:139], v[208:211], v[32:35]
	v_mfma_f32_16x16x32_bf16 v[28:31], v[144:147], v[208:211], v[28:31]
	v_mfma_f32_16x16x32_bf16 v[16:19], v[136:139], v[222:225], v[16:19]
	v_mfma_f32_16x16x32_bf16 v[12:15], v[144:147], v[222:225], v[12:15]
	v_mfma_f32_16x16x32_bf16 v[56:59], v[148:151], v[188:191], v[56:59]
	v_mfma_f32_16x16x32_bf16 v[52:55], v[168:171], v[188:191], v[52:55]
	v_mfma_f32_16x16x32_bf16 v[40:43], v[148:151], v[196:199], v[40:43]
	v_mfma_f32_16x16x32_bf16 v[36:39], v[168:171], v[196:199], v[36:39]
	v_mfma_f32_16x16x32_bf16 v[24:27], v[148:151], v[204:207], v[24:27]
	v_mfma_f32_16x16x32_bf16 v[20:23], v[168:171], v[204:207], v[20:23]
	v_mfma_f32_16x16x32_bf16 v[8:11], v[148:151], v[212:215], v[8:11]
	v_mfma_f32_16x16x32_bf16 v[4:7], v[168:171], v[212:215], v[4:7]
	v_mfma_f32_16x16x32_bf16 v[56:59], v[164:167], v[192:195], v[56:59]
	v_mfma_f32_16x16x32_bf16 v[52:55], v[184:187], v[192:195], v[52:55]
	v_mfma_f32_16x16x32_bf16 v[40:43], v[164:167], v[200:203], v[40:43]
	v_mfma_f32_16x16x32_bf16 v[36:39], v[184:187], v[200:203], v[36:39]
	v_mfma_f32_16x16x32_bf16 v[24:27], v[164:167], v[208:211], v[24:27]
	v_mfma_f32_16x16x32_bf16 v[20:23], v[184:187], v[208:211], v[20:23]
	v_mfma_f32_16x16x32_bf16 v[8:11], v[164:167], v[222:225], v[8:11]
	v_mfma_f32_16x16x32_bf16 v[4:7], v[184:187], v[222:225], v[4:7]
	s_barrier

	s_add_i32 s94, 0, 0x18000
	s_add_i32 s95, 0, 0x1c000
	ds_read_b128 v[132:135], v175
	ds_read_b128 v[136:139], v175 offset:1024
	ds_read_b128 v[140:143], v175 offset:2048
	ds_read_b128 v[144:147], v175 offset:3072
	ds_read_b128 v[148:151], v182
	ds_read_b128 v[164:167], v182 offset:1024
	ds_read_b128 v[168:171], v182 offset:2048
	ds_read_b128 v[184:187], v182 offset:3072
	s_add_u32 s16, s46, 0x80000
	s_addc_u32 s17, s47, 0
	s_mov_b32 m0, s50
	ds_read_b128 v[188:191], v221 offset:32768
	ds_read_b128 v[192:195], v221 offset:33792
	ds_read_b128 v[196:199], v221 offset:34816
	ds_read_b128 v[200:203], v221 offset:35840
	ds_read_b128 v[204:207], v221 offset:36864
	ds_read_b128 v[208:211], v221 offset:37888
	ds_read_b128 v[212:215], v221 offset:38912
	ds_read_b128 v[222:225], v221 offset:39936
	global_load_lds_dwordx4 v156, s[16:17]
	s_mov_b32 m0, s51
	s_nop 0
	global_load_lds_dwordx4 v154, s[16:17]
	s_waitcnt vmcnt(8)
	s_waitcnt lgkmcnt(0)

	s_barrier
	v_mfma_f32_16x16x32_bf16 v[128:131], v[132:135], v[188:191], v[128:131]
	v_mfma_f32_16x16x32_bf16 v[124:127], v[140:143], v[188:191], v[124:127]
	v_mfma_f32_16x16x32_bf16 v[112:115], v[132:135], v[196:199], v[112:115]
	v_mfma_f32_16x16x32_bf16 v[108:111], v[140:143], v[196:199], v[108:111]
	v_mfma_f32_16x16x32_bf16 v[96:99], v[132:135], v[204:207], v[96:99]
	v_mfma_f32_16x16x32_bf16 v[92:95], v[140:143], v[204:207], v[92:95]
	v_mfma_f32_16x16x32_bf16 v[80:83], v[132:135], v[212:215], v[80:83]
	v_mfma_f32_16x16x32_bf16 v[76:79], v[140:143], v[212:215], v[76:79]
	v_mfma_f32_16x16x32_bf16 v[128:131], v[136:139], v[192:195], v[128:131]
	v_mfma_f32_16x16x32_bf16 v[124:127], v[144:147], v[192:195], v[124:127]
	v_mfma_f32_16x16x32_bf16 v[112:115], v[136:139], v[200:203], v[112:115]
	v_mfma_f32_16x16x32_bf16 v[108:111], v[144:147], v[200:203], v[108:111]
	v_mfma_f32_16x16x32_bf16 v[96:99], v[136:139], v[208:211], v[96:99]
	v_mfma_f32_16x16x32_bf16 v[92:95], v[144:147], v[208:211], v[92:95]
	v_mfma_f32_16x16x32_bf16 v[80:83], v[136:139], v[222:225], v[80:83]
	v_mfma_f32_16x16x32_bf16 v[76:79], v[144:147], v[222:225], v[76:79]
	v_mfma_f32_16x16x32_bf16 v[120:123], v[148:151], v[188:191], v[120:123]
	v_mfma_f32_16x16x32_bf16 v[116:119], v[168:171], v[188:191], v[116:119]
	v_mfma_f32_16x16x32_bf16 v[104:107], v[148:151], v[196:199], v[104:107]
	v_mfma_f32_16x16x32_bf16 v[100:103], v[168:171], v[196:199], v[100:103]
	v_mfma_f32_16x16x32_bf16 v[88:91], v[148:151], v[204:207], v[88:91]
	v_mfma_f32_16x16x32_bf16 v[84:87], v[168:171], v[204:207], v[84:87]
	v_mfma_f32_16x16x32_bf16 v[72:75], v[148:151], v[212:215], v[72:75]
	v_mfma_f32_16x16x32_bf16 v[68:71], v[168:171], v[212:215], v[68:71]
	v_mfma_f32_16x16x32_bf16 v[120:123], v[164:167], v[192:195], v[120:123]
	v_mfma_f32_16x16x32_bf16 v[116:119], v[184:187], v[192:195], v[116:119]
	v_mfma_f32_16x16x32_bf16 v[104:107], v[164:167], v[200:203], v[104:107]
	v_mfma_f32_16x16x32_bf16 v[100:103], v[184:187], v[200:203], v[100:103]
	v_mfma_f32_16x16x32_bf16 v[88:91], v[164:167], v[208:211], v[88:91]
	v_mfma_f32_16x16x32_bf16 v[84:87], v[184:187], v[208:211], v[84:87]
	v_mfma_f32_16x16x32_bf16 v[72:75], v[164:167], v[222:225], v[72:75]
	v_mfma_f32_16x16x32_bf16 v[68:71], v[184:187], v[222:225], v[68:71]
	s_barrier

	s_add_i32 s16, s94, s33
	s_mov_b32 m0, s16
	ds_read_b128 v[188:191], v221 offset:49152
	ds_read_b128 v[192:195], v221 offset:50176
	ds_read_b128 v[196:199], v221 offset:51200
	ds_read_b128 v[200:203], v221 offset:52224
	ds_read_b128 v[204:207], v221 offset:53248
	ds_read_b128 v[208:211], v221 offset:54272
	ds_read_b128 v[212:215], v221 offset:55296
	ds_read_b128 v[222:225], v221 offset:56320
	s_add_u32 s100, s28, s24
	s_addc_u32 s101, s29, s25
	global_load_lds_dwordx4 v2, s[100:101]
	s_add_i32 m0, s16, 0x2000
	s_add_u32 s16, s28, 0x80080
	s_addc_u32 s17, s29, 0
	s_add_i32 s28, s95, s33
	global_load_lds_dwordx4 v152, s[100:101]
	s_mov_b32 m0, s28
	s_nop 0
	global_load_lds_dwordx4 v2, s[16:17]
	s_add_i32 m0, s28, 0x2000
	s_nop 0
	global_load_lds_dwordx4 v152, s[16:17]
	s_mov_b32 m0, s72
	s_nop 0
	s_add_u32 s100, s46, s24
	s_addc_u32 s101, s47, s25
	global_load_lds_dwordx4 v156, s[100:101]
	s_mov_b32 m0, s73
	s_nop 0
	global_load_lds_dwordx4 v154, s[100:101]
	s_waitcnt vmcnt(8)
	s_waitcnt lgkmcnt(0)

	s_barrier
	v_mfma_f32_16x16x32_bf16 v[64:67], v[132:135], v[188:191], v[64:67]
	v_mfma_f32_16x16x32_bf16 v[60:63], v[140:143], v[188:191], v[60:63]
	v_mfma_f32_16x16x32_bf16 v[48:51], v[132:135], v[196:199], v[48:51]
	v_mfma_f32_16x16x32_bf16 v[44:47], v[140:143], v[196:199], v[44:47]
	v_mfma_f32_16x16x32_bf16 v[32:35], v[132:135], v[204:207], v[32:35]
	v_mfma_f32_16x16x32_bf16 v[28:31], v[140:143], v[204:207], v[28:31]
	v_mfma_f32_16x16x32_bf16 v[16:19], v[132:135], v[212:215], v[16:19]
	v_mfma_f32_16x16x32_bf16 v[12:15], v[140:143], v[212:215], v[12:15]
	v_mfma_f32_16x16x32_bf16 v[64:67], v[136:139], v[192:195], v[64:67]
	v_mfma_f32_16x16x32_bf16 v[60:63], v[144:147], v[192:195], v[60:63]
	v_mfma_f32_16x16x32_bf16 v[48:51], v[136:139], v[200:203], v[48:51]
	v_mfma_f32_16x16x32_bf16 v[44:47], v[144:147], v[200:203], v[44:47]
	v_mfma_f32_16x16x32_bf16 v[32:35], v[136:139], v[208:211], v[32:35]
	v_mfma_f32_16x16x32_bf16 v[28:31], v[144:147], v[208:211], v[28:31]
	v_mfma_f32_16x16x32_bf16 v[16:19], v[136:139], v[222:225], v[16:19]
	v_mfma_f32_16x16x32_bf16 v[12:15], v[144:147], v[222:225], v[12:15]
	v_mfma_f32_16x16x32_bf16 v[56:59], v[148:151], v[188:191], v[56:59]
	v_mfma_f32_16x16x32_bf16 v[52:55], v[168:171], v[188:191], v[52:55]
	v_mfma_f32_16x16x32_bf16 v[40:43], v[148:151], v[196:199], v[40:43]
	v_mfma_f32_16x16x32_bf16 v[36:39], v[168:171], v[196:199], v[36:39]
	v_mfma_f32_16x16x32_bf16 v[24:27], v[148:151], v[204:207], v[24:27]
	v_mfma_f32_16x16x32_bf16 v[20:23], v[168:171], v[204:207], v[20:23]
	v_mfma_f32_16x16x32_bf16 v[8:11], v[148:151], v[212:215], v[8:11]
	v_mfma_f32_16x16x32_bf16 v[4:7], v[168:171], v[212:215], v[4:7]
	v_mfma_f32_16x16x32_bf16 v[56:59], v[164:167], v[192:195], v[56:59]
	v_mfma_f32_16x16x32_bf16 v[52:55], v[184:187], v[192:195], v[52:55]
	v_mfma_f32_16x16x32_bf16 v[40:43], v[164:167], v[200:203], v[40:43]
	v_mfma_f32_16x16x32_bf16 v[36:39], v[184:187], v[200:203], v[36:39]
	v_mfma_f32_16x16x32_bf16 v[24:27], v[164:167], v[208:211], v[24:27]
	v_mfma_f32_16x16x32_bf16 v[20:23], v[184:187], v[208:211], v[20:23]
	v_mfma_f32_16x16x32_bf16 v[8:11], v[164:167], v[222:225], v[8:11]
	v_mfma_f32_16x16x32_bf16 v[4:7], v[184:187], v[222:225], v[4:7]
	s_barrier

	s_add_i32 vcc_lo, vcc_lo, 2
	s_add_u32 s44, s44, 0x100
	s_addc_u32 s45, s45, 0
	s_add_u32 s91, s91, 0x100
	s_addc_u32 s96, s96, 0
	s_cmp_gt_u32 vcc_lo, 29
	s_cbranch_scc0 .LBB0_446
	s_setprio 0
	v_mov_b32_e32 v250, 0xc2000000
	v_mov_b32_e32 v1, 0xbfb8aa3b
	v_mov_b64_e32 v[238:239], v[236:237]

.Lsp_790:
	v_add_u32_e32 v174, 0x10000, v244
	v_add_u32_e32 v175, 0x14000, v244
	v_add_u32_e32 v176, 0x18000, v244
	v_add_u32_e32 v177, 0x1c000, v244
.LBB0_790:
	s_add_u32 s11, vcc_lo, 0xfff80080
	s_addc_u32 s16, vcc_hi, -1
	s_add_i32 s17, 0, 0x10000
	s_cmp_eq_u32 s10, 28
	s_cselect_b32 s73, s19, s16
	s_cselect_b32 s72, s31, s11
	s_cselect_b32 s29, s23, s49
	s_cselect_b32 s28, s33, s48
	s_add_i32 s11, 0, 0x14000
	ds_read_b128 v[132:135], v174
	ds_read_b128 v[136:139], v174 offset:1024
	ds_read_b128 v[140:143], v174 offset:2048
	ds_read_b128 v[144:147], v174 offset:3072
	ds_read_b128 v[148:151], v175
	ds_read_b128 v[152:155], v175 offset:1024
	ds_read_b128 v[156:159], v175 offset:2048
	ds_read_b128 v[160:163], v175 offset:3072
	s_add_i32 m0, s77, 0xc000
	ds_read_b128 v[164:167], v246
	ds_read_b128 v[188:191], v246 offset:1024
	ds_read_b128 v[192:195], v246 offset:2048
	ds_read_b128 v[196:199], v246 offset:3072
	ds_read_b128 v[200:203], v246 offset:4096
	ds_read_b128 v[204:207], v246 offset:5120
	ds_read_b128 v[208:211], v246 offset:6144
	ds_read_b128 v[212:215], v246 offset:7168
	global_load_lds_dwordx4 v184, vcc
	s_add_i32 m0, s77, 0xe000
	s_nop 0
	global_load_lds_dwordx4 v186, vcc
	s_waitcnt vmcnt(8)
	s_waitcnt lgkmcnt(0)

	s_barrier
	v_mfma_f32_16x16x32_bf16 v[128:131], v[132:135], v[164:167], v[128:131]
	v_mfma_f32_16x16x32_bf16 v[124:127], v[140:143], v[164:167], v[124:127]
	v_mfma_f32_16x16x32_bf16 v[112:115], v[132:135], v[192:195], v[112:115]
	v_mfma_f32_16x16x32_bf16 v[108:111], v[140:143], v[192:195], v[108:111]
	v_mfma_f32_16x16x32_bf16 v[96:99], v[132:135], v[200:203], v[96:99]
	v_mfma_f32_16x16x32_bf16 v[92:95], v[140:143], v[200:203], v[92:95]
	v_mfma_f32_16x16x32_bf16 v[80:83], v[132:135], v[208:211], v[80:83]
	v_mfma_f32_16x16x32_bf16 v[76:79], v[140:143], v[208:211], v[76:79]
	v_mfma_f32_16x16x32_bf16 v[128:131], v[136:139], v[188:191], v[128:131]
	v_mfma_f32_16x16x32_bf16 v[124:127], v[144:147], v[188:191], v[124:127]
	v_mfma_f32_16x16x32_bf16 v[112:115], v[136:139], v[196:199], v[112:115]
	v_mfma_f32_16x16x32_bf16 v[108:111], v[144:147], v[196:199], v[108:111]
	v_mfma_f32_16x16x32_bf16 v[96:99], v[136:139], v[204:207], v[96:99]
	v_mfma_f32_16x16x32_bf16 v[92:95], v[144:147], v[204:207], v[92:95]
	v_mfma_f32_16x16x32_bf16 v[80:83], v[136:139], v[212:215], v[80:83]
	v_mfma_f32_16x16x32_bf16 v[76:79], v[144:147], v[212:215], v[76:79]
	v_mfma_f32_16x16x32_bf16 v[120:123], v[148:151], v[164:167], v[120:123]
	v_mfma_f32_16x16x32_bf16 v[116:119], v[156:159], v[164:167], v[116:119]
	v_mfma_f32_16x16x32_bf16 v[104:107], v[148:151], v[192:195], v[104:107]
	v_mfma_f32_16x16x32_bf16 v[100:103], v[156:159], v[192:195], v[100:103]
	v_mfma_f32_16x16x32_bf16 v[88:91], v[148:151], v[200:203], v[88:91]
	v_mfma_f32_16x16x32_bf16 v[84:87], v[156:159], v[200:203], v[84:87]
	v_mfma_f32_16x16x32_bf16 v[72:75], v[148:151], v[208:211], v[72:75]
	v_mfma_f32_16x16x32_bf16 v[68:71], v[156:159], v[208:211], v[68:71]
	v_mfma_f32_16x16x32_bf16 v[120:123], v[152:155], v[188:191], v[120:123]
	v_mfma_f32_16x16x32_bf16 v[116:119], v[160:163], v[188:191], v[116:119]
	v_mfma_f32_16x16x32_bf16 v[104:107], v[152:155], v[196:199], v[104:107]
	v_mfma_f32_16x16x32_bf16 v[100:103], v[160:163], v[196:199], v[100:103]
	v_mfma_f32_16x16x32_bf16 v[88:91], v[152:155], v[204:207], v[88:91]
	v_mfma_f32_16x16x32_bf16 v[84:87], v[160:163], v[204:207], v[84:87]
	v_mfma_f32_16x16x32_bf16 v[72:75], v[152:155], v[212:215], v[72:75]
	v_mfma_f32_16x16x32_bf16 v[68:71], v[160:163], v[212:215], v[68:71]
	s_barrier

	s_add_i32 s16, s17, s74
	s_mov_b32 m0, s16
	ds_read_b128 v[164:167], v246 offset:16384
	ds_read_b128 v[188:191], v246 offset:17408
	ds_read_b128 v[192:195], v246 offset:18432
	ds_read_b128 v[196:199], v246 offset:19456
	ds_read_b128 v[200:203], v246 offset:20480
	ds_read_b128 v[204:207], v246 offset:21504
	ds_read_b128 v[208:211], v246 offset:22528
	ds_read_b128 v[212:215], v246 offset:23552
	global_load_lds_dwordx4 v2, s[28:29]
	s_add_i32 m0, s16, 0x2000
	s_add_u32 s16, s28, 0x20000
	s_addc_u32 s17, s29, 0
	s_add_i32 s11, s11, s74
	global_load_lds_dwordx4 v168, s[28:29]
	s_mov_b32 m0, s11
	s_nop 0
	global_load_lds_dwordx4 v2, s[16:17]
	s_add_i32 m0, s11, 0x2000
	s_nop 0
	global_load_lds_dwordx4 v168, s[16:17]
	s_mov_b32 m0, s77
	s_nop 0
	global_load_lds_dwordx4 v172, s[72:73]
	s_mov_b32 m0, s78
	s_nop 0
	global_load_lds_dwordx4 v170, s[72:73]
	s_waitcnt vmcnt(8)
	s_waitcnt lgkmcnt(0)

	s_barrier
	v_mfma_f32_16x16x32_bf16 v[64:67], v[132:135], v[164:167], v[64:67]
	v_mfma_f32_16x16x32_bf16 v[60:63], v[140:143], v[164:167], v[60:63]
	v_mfma_f32_16x16x32_bf16 v[48:51], v[132:135], v[192:195], v[48:51]
	v_mfma_f32_16x16x32_bf16 v[44:47], v[140:143], v[192:195], v[44:47]
	v_mfma_f32_16x16x32_bf16 v[32:35], v[132:135], v[200:203], v[32:35]
	v_mfma_f32_16x16x32_bf16 v[28:31], v[140:143], v[200:203], v[28:31]
	v_mfma_f32_16x16x32_bf16 v[16:19], v[132:135], v[208:211], v[16:19]
	v_mfma_f32_16x16x32_bf16 v[12:15], v[140:143], v[208:211], v[12:15]
	v_mfma_f32_16x16x32_bf16 v[64:67], v[136:139], v[188:191], v[64:67]
	v_mfma_f32_16x16x32_bf16 v[60:63], v[144:147], v[188:191], v[60:63]
	v_mfma_f32_16x16x32_bf16 v[48:51], v[136:139], v[196:199], v[48:51]
	v_mfma_f32_16x16x32_bf16 v[44:47], v[144:147], v[196:199], v[44:47]
	v_mfma_f32_16x16x32_bf16 v[32:35], v[136:139], v[204:207], v[32:35]
	v_mfma_f32_16x16x32_bf16 v[28:31], v[144:147], v[204:207], v[28:31]
	v_mfma_f32_16x16x32_bf16 v[16:19], v[136:139], v[212:215], v[16:19]
	v_mfma_f32_16x16x32_bf16 v[12:15], v[144:147], v[212:215], v[12:15]
	v_mfma_f32_16x16x32_bf16 v[56:59], v[148:151], v[164:167], v[56:59]
	v_mfma_f32_16x16x32_bf16 v[52:55], v[156:159], v[164:167], v[52:55]
	v_mfma_f32_16x16x32_bf16 v[40:43], v[148:151], v[192:195], v[40:43]
	v_mfma_f32_16x16x32_bf16 v[36:39], v[156:159], v[192:195], v[36:39]
	v_mfma_f32_16x16x32_bf16 v[24:27], v[148:151], v[200:203], v[24:27]
	v_mfma_f32_16x16x32_bf16 v[20:23], v[156:159], v[200:203], v[20:23]
	v_mfma_f32_16x16x32_bf16 v[8:11], v[148:151], v[208:211], v[8:11]
	v_mfma_f32_16x16x32_bf16 v[4:7], v[156:159], v[208:211], v[4:7]
	v_mfma_f32_16x16x32_bf16 v[56:59], v[152:155], v[188:191], v[56:59]
	v_mfma_f32_16x16x32_bf16 v[52:55], v[160:163], v[188:191], v[52:55]
	v_mfma_f32_16x16x32_bf16 v[40:43], v[152:155], v[196:199], v[40:43]
	v_mfma_f32_16x16x32_bf16 v[36:39], v[160:163], v[196:199], v[36:39]
	v_mfma_f32_16x16x32_bf16 v[24:27], v[152:155], v[204:207], v[24:27]
	v_mfma_f32_16x16x32_bf16 v[20:23], v[160:163], v[204:207], v[20:23]
	v_mfma_f32_16x16x32_bf16 v[8:11], v[152:155], v[212:215], v[8:11]
	v_mfma_f32_16x16x32_bf16 v[4:7], v[160:163], v[212:215], v[4:7]
	s_barrier

	s_add_i32 s11, 0, 0x18000
	s_add_i32 s94, 0, 0x1c000
	ds_read_b128 v[132:135], v176
	ds_read_b128 v[136:139], v176 offset:1024
	ds_read_b128 v[140:143], v176 offset:2048
	ds_read_b128 v[144:147], v176 offset:3072
	ds_read_b128 v[148:151], v177
	ds_read_b128 v[152:155], v177 offset:1024
	ds_read_b128 v[156:159], v177 offset:2048
	ds_read_b128 v[160:163], v177 offset:3072
	s_add_u32 s16, s72, 0x80000
	s_addc_u32 s17, s73, 0
	s_mov_b32 m0, s95
	ds_read_b128 v[164:167], v246 offset:32768
	ds_read_b128 v[188:191], v246 offset:33792
	ds_read_b128 v[192:195], v246 offset:34816
	ds_read_b128 v[196:199], v246 offset:35840
	ds_read_b128 v[200:203], v246 offset:36864
	ds_read_b128 v[204:207], v246 offset:37888
	ds_read_b128 v[208:211], v246 offset:38912
	ds_read_b128 v[212:215], v246 offset:39936
	global_load_lds_dwordx4 v172, s[16:17]
	s_mov_b32 m0, s68
	s_nop 0
	global_load_lds_dwordx4 v170, s[16:17]
	s_waitcnt vmcnt(8)
	s_waitcnt lgkmcnt(0)

	s_barrier
	v_mfma_f32_16x16x32_bf16 v[128:131], v[132:135], v[164:167], v[128:131]
	v_mfma_f32_16x16x32_bf16 v[124:127], v[140:143], v[164:167], v[124:127]
	v_mfma_f32_16x16x32_bf16 v[112:115], v[132:135], v[192:195], v[112:115]
	v_mfma_f32_16x16x32_bf16 v[108:111], v[140:143], v[192:195], v[108:111]
	v_mfma_f32_16x16x32_bf16 v[96:99], v[132:135], v[200:203], v[96:99]
	v_mfma_f32_16x16x32_bf16 v[92:95], v[140:143], v[200:203], v[92:95]
	v_mfma_f32_16x16x32_bf16 v[80:83], v[132:135], v[208:211], v[80:83]
	v_mfma_f32_16x16x32_bf16 v[76:79], v[140:143], v[208:211], v[76:79]
	v_mfma_f32_16x16x32_bf16 v[128:131], v[136:139], v[188:191], v[128:131]
	v_mfma_f32_16x16x32_bf16 v[124:127], v[144:147], v[188:191], v[124:127]
	v_mfma_f32_16x16x32_bf16 v[112:115], v[136:139], v[196:199], v[112:115]
	v_mfma_f32_16x16x32_bf16 v[108:111], v[144:147], v[196:199], v[108:111]
	v_mfma_f32_16x16x32_bf16 v[96:99], v[136:139], v[204:207], v[96:99]
	v_mfma_f32_16x16x32_bf16 v[92:95], v[144:147], v[204:207], v[92:95]
	v_mfma_f32_16x16x32_bf16 v[80:83], v[136:139], v[212:215], v[80:83]
	v_mfma_f32_16x16x32_bf16 v[76:79], v[144:147], v[212:215], v[76:79]
	v_mfma_f32_16x16x32_bf16 v[120:123], v[148:151], v[164:167], v[120:123]
	v_mfma_f32_16x16x32_bf16 v[116:119], v[156:159], v[164:167], v[116:119]
	v_mfma_f32_16x16x32_bf16 v[104:107], v[148:151], v[192:195], v[104:107]
	v_mfma_f32_16x16x32_bf16 v[100:103], v[156:159], v[192:195], v[100:103]
	v_mfma_f32_16x16x32_bf16 v[88:91], v[148:151], v[200:203], v[88:91]
	v_mfma_f32_16x16x32_bf16 v[84:87], v[156:159], v[200:203], v[84:87]
	v_mfma_f32_16x16x32_bf16 v[72:75], v[148:151], v[208:211], v[72:75]
	v_mfma_f32_16x16x32_bf16 v[68:71], v[156:159], v[208:211], v[68:71]
	v_mfma_f32_16x16x32_bf16 v[120:123], v[152:155], v[188:191], v[120:123]
	v_mfma_f32_16x16x32_bf16 v[116:119], v[160:163], v[188:191], v[116:119]
	v_mfma_f32_16x16x32_bf16 v[104:107], v[152:155], v[196:199], v[104:107]
	v_mfma_f32_16x16x32_bf16 v[100:103], v[160:163], v[196:199], v[100:103]
	v_mfma_f32_16x16x32_bf16 v[88:91], v[152:155], v[204:207], v[88:91]
	v_mfma_f32_16x16x32_bf16 v[84:87], v[160:163], v[204:207], v[84:87]
	v_mfma_f32_16x16x32_bf16 v[72:75], v[152:155], v[212:215], v[72:75]
	v_mfma_f32_16x16x32_bf16 v[68:71], v[160:163], v[212:215], v[68:71]
	s_barrier

	s_add_i32 s11, s11, s74
	s_mov_b32 m0, s11
	ds_read_b128 v[164:167], v246 offset:49152
	ds_read_b128 v[188:191], v246 offset:50176
	ds_read_b128 v[192:195], v246 offset:51200
	ds_read_b128 v[196:199], v246 offset:52224
	ds_read_b128 v[200:203], v246 offset:53248
	ds_read_b128 v[204:207], v246 offset:54272
	ds_read_b128 v[208:211], v246 offset:55296
	ds_read_b128 v[212:215], v246 offset:56320
	s_add_u32 s100, s28, s24
	s_addc_u32 s101, s29, s25
	global_load_lds_dwordx4 v2, s[100:101]
	s_add_i32 m0, s11, 0x2000
	s_add_u32 s16, s28, 0x20080
	s_addc_u32 s17, s29, 0
	s_add_i32 s11, s94, s74
	global_load_lds_dwordx4 v168, s[100:101]
	s_mov_b32 m0, s11
	s_nop 0
	global_load_lds_dwordx4 v2, s[16:17]
	s_add_i32 m0, s11, 0x2000
	s_nop 0
	global_load_lds_dwordx4 v168, s[16:17]
	s_mov_b32 m0, s96
	s_nop 0
	s_add_u32 s100, s72, s24
	s_addc_u32 s101, s73, s25
	global_load_lds_dwordx4 v172, s[100:101]
	s_mov_b32 m0, s3
	s_nop 0
	global_load_lds_dwordx4 v170, s[100:101]
	s_waitcnt vmcnt(8)
	s_waitcnt lgkmcnt(0)

	s_barrier
	v_mfma_f32_16x16x32_bf16 v[64:67], v[132:135], v[164:167], v[64:67]
	v_mfma_f32_16x16x32_bf16 v[60:63], v[140:143], v[164:167], v[60:63]
	v_mfma_f32_16x16x32_bf16 v[48:51], v[132:135], v[192:195], v[48:51]
	v_mfma_f32_16x16x32_bf16 v[44:47], v[140:143], v[192:195], v[44:47]
	v_mfma_f32_16x16x32_bf16 v[32:35], v[132:135], v[200:203], v[32:35]
	v_mfma_f32_16x16x32_bf16 v[28:31], v[140:143], v[200:203], v[28:31]
	v_mfma_f32_16x16x32_bf16 v[16:19], v[132:135], v[208:211], v[16:19]
	v_mfma_f32_16x16x32_bf16 v[12:15], v[140:143], v[208:211], v[12:15]
	v_mfma_f32_16x16x32_bf16 v[64:67], v[136:139], v[188:191], v[64:67]
	v_mfma_f32_16x16x32_bf16 v[60:63], v[144:147], v[188:191], v[60:63]
	v_mfma_f32_16x16x32_bf16 v[48:51], v[136:139], v[196:199], v[48:51]
	v_mfma_f32_16x16x32_bf16 v[44:47], v[144:147], v[196:199], v[44:47]
	v_mfma_f32_16x16x32_bf16 v[32:35], v[136:139], v[204:207], v[32:35]
	v_mfma_f32_16x16x32_bf16 v[28:31], v[144:147], v[204:207], v[28:31]
	v_mfma_f32_16x16x32_bf16 v[16:19], v[136:139], v[212:215], v[16:19]
	v_mfma_f32_16x16x32_bf16 v[12:15], v[144:147], v[212:215], v[12:15]
	v_mfma_f32_16x16x32_bf16 v[56:59], v[148:151], v[164:167], v[56:59]
	v_mfma_f32_16x16x32_bf16 v[52:55], v[156:159], v[164:167], v[52:55]
	v_mfma_f32_16x16x32_bf16 v[40:43], v[148:151], v[192:195], v[40:43]
	v_mfma_f32_16x16x32_bf16 v[36:39], v[156:159], v[192:195], v[36:39]
	v_mfma_f32_16x16x32_bf16 v[24:27], v[148:151], v[200:203], v[24:27]
	v_mfma_f32_16x16x32_bf16 v[20:23], v[156:159], v[200:203], v[20:23]
	v_mfma_f32_16x16x32_bf16 v[8:11], v[148:151], v[208:211], v[8:11]
	v_mfma_f32_16x16x32_bf16 v[4:7], v[156:159], v[208:211], v[4:7]
	v_mfma_f32_16x16x32_bf16 v[56:59], v[152:155], v[188:191], v[56:59]
	v_mfma_f32_16x16x32_bf16 v[52:55], v[160:163], v[188:191], v[52:55]
	v_mfma_f32_16x16x32_bf16 v[40:43], v[152:155], v[196:199], v[40:43]
	v_mfma_f32_16x16x32_bf16 v[36:39], v[160:163], v[196:199], v[36:39]
	v_mfma_f32_16x16x32_bf16 v[24:27], v[152:155], v[204:207], v[24:27]
	v_mfma_f32_16x16x32_bf16 v[20:23], v[160:163], v[204:207], v[20:23]
	v_mfma_f32_16x16x32_bf16 v[8:11], v[152:155], v[212:215], v[8:11]
	v_mfma_f32_16x16x32_bf16 v[4:7], v[160:163], v[212:215], v[4:7]
	s_barrier

	s_add_i32 s10, s10, 2
	s_add_u32 vcc_lo, vcc_lo, 0x100
	s_addc_u32 vcc_hi, vcc_hi, 0
	s_add_u32 s48, s48, 0x100
	s_addc_u32 s49, s49, 0
	s_cmp_gt_u32 s10, 29
	s_cbranch_scc0 .LBB0_790
	s_setprio 0
	v_readlane_b32 s10, v252, 2
	v_readlane_b32 s11, v252, 3

.Lsp_870:
	v_add_u32_e32 v174, 0x10000, v227
	v_add_u32_e32 v175, 0x14000, v227
	v_add_u32_e32 v176, 0x18000, v227
	v_add_u32_e32 v177, 0x1c000, v227
.LBB0_870:
	s_add_u32 s16, s44, 0xfff80080
	s_addc_u32 s17, s45, -1
	s_add_i32 s94, 0, 0x10000
	s_cmp_eq_u32 vcc_lo, 28
	s_cselect_b32 s47, s37, s17
	s_cselect_b32 s46, s88, s16
	s_cselect_b32 s29, s27, s96
	s_cselect_b32 s28, s89, s91
	s_add_i32 s95, 0, 0x14000
	ds_read_b128 v[132:135], v174
	ds_read_b128 v[136:139], v174 offset:1024
	ds_read_b128 v[140:143], v174 offset:2048
	ds_read_b128 v[144:147], v174 offset:3072
	ds_read_b128 v[148:151], v175
	ds_read_b128 v[152:155], v175 offset:1024
	ds_read_b128 v[166:169], v175 offset:2048
	ds_read_b128 v[170:173], v175 offset:3072
	s_add_i32 m0, s48, 0xc000
	ds_read_b128 v[184:187], v229
	ds_read_b128 v[188:191], v229 offset:1024
	ds_read_b128 v[192:195], v229 offset:2048
	ds_read_b128 v[196:199], v229 offset:3072
	ds_read_b128 v[200:203], v229 offset:4096
	ds_read_b128 v[204:207], v229 offset:5120
	ds_read_b128 v[208:211], v229 offset:6144
	ds_read_b128 v[212:215], v229 offset:7168
	global_load_lds_dwordx4 v162, s[44:45]
	s_add_i32 m0, s48, 0xe000
	s_nop 0
	global_load_lds_dwordx4 v164, s[44:45]
	s_waitcnt vmcnt(8)
	s_waitcnt lgkmcnt(0)

	s_barrier
	v_mfma_f32_16x16x32_bf16 v[128:131], v[132:135], v[184:187], v[128:131]
	v_mfma_f32_16x16x32_bf16 v[124:127], v[140:143], v[184:187], v[124:127]
	v_mfma_f32_16x16x32_bf16 v[112:115], v[132:135], v[192:195], v[112:115]
	v_mfma_f32_16x16x32_bf16 v[108:111], v[140:143], v[192:195], v[108:111]
	v_mfma_f32_16x16x32_bf16 v[96:99], v[132:135], v[200:203], v[96:99]
	v_mfma_f32_16x16x32_bf16 v[92:95], v[140:143], v[200:203], v[92:95]
	v_mfma_f32_16x16x32_bf16 v[80:83], v[132:135], v[208:211], v[80:83]
	v_mfma_f32_16x16x32_bf16 v[76:79], v[140:143], v[208:211], v[76:79]
	v_mfma_f32_16x16x32_bf16 v[128:131], v[136:139], v[188:191], v[128:131]
	v_mfma_f32_16x16x32_bf16 v[124:127], v[144:147], v[188:191], v[124:127]
	v_mfma_f32_16x16x32_bf16 v[112:115], v[136:139], v[196:199], v[112:115]
	v_mfma_f32_16x16x32_bf16 v[108:111], v[144:147], v[196:199], v[108:111]
	v_mfma_f32_16x16x32_bf16 v[96:99], v[136:139], v[204:207], v[96:99]
	v_mfma_f32_16x16x32_bf16 v[92:95], v[144:147], v[204:207], v[92:95]
	v_mfma_f32_16x16x32_bf16 v[80:83], v[136:139], v[212:215], v[80:83]
	v_mfma_f32_16x16x32_bf16 v[76:79], v[144:147], v[212:215], v[76:79]
	v_mfma_f32_16x16x32_bf16 v[120:123], v[148:151], v[184:187], v[120:123]
	v_mfma_f32_16x16x32_bf16 v[116:119], v[166:169], v[184:187], v[116:119]
	v_mfma_f32_16x16x32_bf16 v[104:107], v[148:151], v[192:195], v[104:107]
	v_mfma_f32_16x16x32_bf16 v[100:103], v[166:169], v[192:195], v[100:103]
	v_mfma_f32_16x16x32_bf16 v[88:91], v[148:151], v[200:203], v[88:91]
	v_mfma_f32_16x16x32_bf16 v[84:87], v[166:169], v[200:203], v[84:87]
	v_mfma_f32_16x16x32_bf16 v[72:75], v[148:151], v[208:211], v[72:75]
	v_mfma_f32_16x16x32_bf16 v[68:71], v[166:169], v[208:211], v[68:71]
	v_mfma_f32_16x16x32_bf16 v[120:123], v[152:155], v[188:191], v[120:123]
	v_mfma_f32_16x16x32_bf16 v[116:119], v[170:173], v[188:191], v[116:119]
	v_mfma_f32_16x16x32_bf16 v[104:107], v[152:155], v[196:199], v[104:107]
	v_mfma_f32_16x16x32_bf16 v[100:103], v[170:173], v[196:199], v[100:103]
	v_mfma_f32_16x16x32_bf16 v[88:91], v[152:155], v[204:207], v[88:91]
	v_mfma_f32_16x16x32_bf16 v[84:87], v[170:173], v[204:207], v[84:87]
	v_mfma_f32_16x16x32_bf16 v[72:75], v[152:155], v[212:215], v[72:75]
	v_mfma_f32_16x16x32_bf16 v[68:71], v[170:173], v[212:215], v[68:71]
	s_barrier

	s_add_i32 s16, s94, s33
	s_mov_b32 m0, s16
	ds_read_b128 v[184:187], v229 offset:16384
	ds_read_b128 v[188:191], v229 offset:17408
	ds_read_b128 v[192:195], v229 offset:18432
	ds_read_b128 v[196:199], v229 offset:19456
	ds_read_b128 v[200:203], v229 offset:20480
	ds_read_b128 v[204:207], v229 offset:21504
	ds_read_b128 v[208:211], v229 offset:22528
	ds_read_b128 v[212:215], v229 offset:23552
	global_load_lds_dwordx4 v2, s[28:29]
	s_add_i32 m0, s16, 0x2000
	s_add_u32 s16, s28, 0x80000
	s_addc_u32 s17, s29, 0
	s_add_i32 s94, s95, s33
	global_load_lds_dwordx4 v156, s[28:29]
	s_mov_b32 m0, s94
	s_nop 0
	global_load_lds_dwordx4 v2, s[16:17]
	s_add_i32 m0, s94, 0x2000
	s_nop 0
	global_load_lds_dwordx4 v156, s[16:17]
	s_mov_b32 m0, s48
	s_nop 0
	global_load_lds_dwordx4 v160, s[46:47]
	s_mov_b32 m0, s49
	s_nop 0
	global_load_lds_dwordx4 v158, s[46:47]
	s_waitcnt vmcnt(8)
	s_waitcnt lgkmcnt(0)

	s_barrier
	v_mfma_f32_16x16x32_bf16 v[64:67], v[132:135], v[184:187], v[64:67]
	v_mfma_f32_16x16x32_bf16 v[60:63], v[140:143], v[184:187], v[60:63]
	v_mfma_f32_16x16x32_bf16 v[48:51], v[132:135], v[192:195], v[48:51]
	v_mfma_f32_16x16x32_bf16 v[44:47], v[140:143], v[192:195], v[44:47]
	v_mfma_f32_16x16x32_bf16 v[32:35], v[132:135], v[200:203], v[32:35]
	v_mfma_f32_16x16x32_bf16 v[28:31], v[140:143], v[200:203], v[28:31]
	v_mfma_f32_16x16x32_bf16 v[16:19], v[132:135], v[208:211], v[16:19]
	v_mfma_f32_16x16x32_bf16 v[12:15], v[140:143], v[208:211], v[12:15]
	v_mfma_f32_16x16x32_bf16 v[64:67], v[136:139], v[188:191], v[64:67]
	v_mfma_f32_16x16x32_bf16 v[60:63], v[144:147], v[188:191], v[60:63]
	v_mfma_f32_16x16x32_bf16 v[48:51], v[136:139], v[196:199], v[48:51]
	v_mfma_f32_16x16x32_bf16 v[44:47], v[144:147], v[196:199], v[44:47]
	v_mfma_f32_16x16x32_bf16 v[32:35], v[136:139], v[204:207], v[32:35]
	v_mfma_f32_16x16x32_bf16 v[28:31], v[144:147], v[204:207], v[28:31]
	v_mfma_f32_16x16x32_bf16 v[16:19], v[136:139], v[212:215], v[16:19]
	v_mfma_f32_16x16x32_bf16 v[12:15], v[144:147], v[212:215], v[12:15]
	v_mfma_f32_16x16x32_bf16 v[56:59], v[148:151], v[184:187], v[56:59]
	v_mfma_f32_16x16x32_bf16 v[52:55], v[166:169], v[184:187], v[52:55]
	v_mfma_f32_16x16x32_bf16 v[40:43], v[148:151], v[192:195], v[40:43]
	v_mfma_f32_16x16x32_bf16 v[36:39], v[166:169], v[192:195], v[36:39]
	v_mfma_f32_16x16x32_bf16 v[24:27], v[148:151], v[200:203], v[24:27]
	v_mfma_f32_16x16x32_bf16 v[20:23], v[166:169], v[200:203], v[20:23]
	v_mfma_f32_16x16x32_bf16 v[8:11], v[148:151], v[208:211], v[8:11]
	v_mfma_f32_16x16x32_bf16 v[4:7], v[166:169], v[208:211], v[4:7]
	v_mfma_f32_16x16x32_bf16 v[56:59], v[152:155], v[188:191], v[56:59]
	v_mfma_f32_16x16x32_bf16 v[52:55], v[170:173], v[188:191], v[52:55]
	v_mfma_f32_16x16x32_bf16 v[40:43], v[152:155], v[196:199], v[40:43]
	v_mfma_f32_16x16x32_bf16 v[36:39], v[170:173], v[196:199], v[36:39]
	v_mfma_f32_16x16x32_bf16 v[24:27], v[152:155], v[204:207], v[24:27]
	v_mfma_f32_16x16x32_bf16 v[20:23], v[170:173], v[204:207], v[20:23]
	v_mfma_f32_16x16x32_bf16 v[8:11], v[152:155], v[212:215], v[8:11]
	v_mfma_f32_16x16x32_bf16 v[4:7], v[170:173], v[212:215], v[4:7]
	s_barrier

	s_add_i32 s94, 0, 0x18000
	s_add_i32 s95, 0, 0x1c000
	ds_read_b128 v[132:135], v176
	ds_read_b128 v[136:139], v176 offset:1024
	ds_read_b128 v[140:143], v176 offset:2048
	ds_read_b128 v[144:147], v176 offset:3072
	ds_read_b128 v[148:151], v177
	ds_read_b128 v[152:155], v177 offset:1024
	ds_read_b128 v[166:169], v177 offset:2048
	ds_read_b128 v[170:173], v177 offset:3072
	s_add_u32 s16, s46, 0x80000
	s_addc_u32 s17, s47, 0
	s_mov_b32 m0, s50
	ds_read_b128 v[184:187], v229 offset:32768
	ds_read_b128 v[188:191], v229 offset:33792
	ds_read_b128 v[192:195], v229 offset:34816
	ds_read_b128 v[196:199], v229 offset:35840
	ds_read_b128 v[200:203], v229 offset:36864
	ds_read_b128 v[204:207], v229 offset:37888
	ds_read_b128 v[208:211], v229 offset:38912
	ds_read_b128 v[212:215], v229 offset:39936
	global_load_lds_dwordx4 v160, s[16:17]
	s_mov_b32 m0, s51
	s_nop 0
	global_load_lds_dwordx4 v158, s[16:17]
	s_waitcnt vmcnt(8)
	s_waitcnt lgkmcnt(0)

	s_barrier
	v_mfma_f32_16x16x32_bf16 v[128:131], v[132:135], v[184:187], v[128:131]
	v_mfma_f32_16x16x32_bf16 v[124:127], v[140:143], v[184:187], v[124:127]
	v_mfma_f32_16x16x32_bf16 v[112:115], v[132:135], v[192:195], v[112:115]
	v_mfma_f32_16x16x32_bf16 v[108:111], v[140:143], v[192:195], v[108:111]
	v_mfma_f32_16x16x32_bf16 v[96:99], v[132:135], v[200:203], v[96:99]
	v_mfma_f32_16x16x32_bf16 v[92:95], v[140:143], v[200:203], v[92:95]
	v_mfma_f32_16x16x32_bf16 v[80:83], v[132:135], v[208:211], v[80:83]
	v_mfma_f32_16x16x32_bf16 v[76:79], v[140:143], v[208:211], v[76:79]
	v_mfma_f32_16x16x32_bf16 v[128:131], v[136:139], v[188:191], v[128:131]
	v_mfma_f32_16x16x32_bf16 v[124:127], v[144:147], v[188:191], v[124:127]
	v_mfma_f32_16x16x32_bf16 v[112:115], v[136:139], v[196:199], v[112:115]
	v_mfma_f32_16x16x32_bf16 v[108:111], v[144:147], v[196:199], v[108:111]
	v_mfma_f32_16x16x32_bf16 v[96:99], v[136:139], v[204:207], v[96:99]
	v_mfma_f32_16x16x32_bf16 v[92:95], v[144:147], v[204:207], v[92:95]
	v_mfma_f32_16x16x32_bf16 v[80:83], v[136:139], v[212:215], v[80:83]
	v_mfma_f32_16x16x32_bf16 v[76:79], v[144:147], v[212:215], v[76:79]
	v_mfma_f32_16x16x32_bf16 v[120:123], v[148:151], v[184:187], v[120:123]
	v_mfma_f32_16x16x32_bf16 v[116:119], v[166:169], v[184:187], v[116:119]
	v_mfma_f32_16x16x32_bf16 v[104:107], v[148:151], v[192:195], v[104:107]
	v_mfma_f32_16x16x32_bf16 v[100:103], v[166:169], v[192:195], v[100:103]
	v_mfma_f32_16x16x32_bf16 v[88:91], v[148:151], v[200:203], v[88:91]
	v_mfma_f32_16x16x32_bf16 v[84:87], v[166:169], v[200:203], v[84:87]
	v_mfma_f32_16x16x32_bf16 v[72:75], v[148:151], v[208:211], v[72:75]
	v_mfma_f32_16x16x32_bf16 v[68:71], v[166:169], v[208:211], v[68:71]
	v_mfma_f32_16x16x32_bf16 v[120:123], v[152:155], v[188:191], v[120:123]
	v_mfma_f32_16x16x32_bf16 v[116:119], v[170:173], v[188:191], v[116:119]
	v_mfma_f32_16x16x32_bf16 v[104:107], v[152:155], v[196:199], v[104:107]
	v_mfma_f32_16x16x32_bf16 v[100:103], v[170:173], v[196:199], v[100:103]
	v_mfma_f32_16x16x32_bf16 v[88:91], v[152:155], v[204:207], v[88:91]
	v_mfma_f32_16x16x32_bf16 v[84:87], v[170:173], v[204:207], v[84:87]
	v_mfma_f32_16x16x32_bf16 v[72:75], v[152:155], v[212:215], v[72:75]
	v_mfma_f32_16x16x32_bf16 v[68:71], v[170:173], v[212:215], v[68:71]
	s_barrier

	s_add_i32 s16, s94, s33
	s_mov_b32 m0, s16
	ds_read_b128 v[184:187], v229 offset:49152
	ds_read_b128 v[188:191], v229 offset:50176
	ds_read_b128 v[192:195], v229 offset:51200
	ds_read_b128 v[196:199], v229 offset:52224
	ds_read_b128 v[200:203], v229 offset:53248
	ds_read_b128 v[204:207], v229 offset:54272
	ds_read_b128 v[208:211], v229 offset:55296
	ds_read_b128 v[212:215], v229 offset:56320
	s_add_u32 s100, s28, s24
	s_addc_u32 s101, s29, s25
	global_load_lds_dwordx4 v2, s[100:101]
	s_add_i32 m0, s16, 0x2000
	s_add_u32 s16, s28, 0x80080
	s_addc_u32 s17, s29, 0
	s_add_i32 s28, s95, s33
	global_load_lds_dwordx4 v156, s[100:101]
	s_mov_b32 m0, s28
	s_nop 0
	global_load_lds_dwordx4 v2, s[16:17]
	s_add_i32 m0, s28, 0x2000
	s_nop 0
	global_load_lds_dwordx4 v156, s[16:17]
	s_mov_b32 m0, s72
	s_nop 0
	s_add_u32 s100, s46, s24
	s_addc_u32 s101, s47, s25
	global_load_lds_dwordx4 v160, s[100:101]
	s_mov_b32 m0, s73
	s_nop 0
	global_load_lds_dwordx4 v158, s[100:101]
	s_waitcnt vmcnt(8)
	s_waitcnt lgkmcnt(0)

	s_barrier
	v_mfma_f32_16x16x32_bf16 v[64:67], v[132:135], v[184:187], v[64:67]
	v_mfma_f32_16x16x32_bf16 v[60:63], v[140:143], v[184:187], v[60:63]
	v_mfma_f32_16x16x32_bf16 v[48:51], v[132:135], v[192:195], v[48:51]
	v_mfma_f32_16x16x32_bf16 v[44:47], v[140:143], v[192:195], v[44:47]
	v_mfma_f32_16x16x32_bf16 v[32:35], v[132:135], v[200:203], v[32:35]
	v_mfma_f32_16x16x32_bf16 v[28:31], v[140:143], v[200:203], v[28:31]
	v_mfma_f32_16x16x32_bf16 v[16:19], v[132:135], v[208:211], v[16:19]
	v_mfma_f32_16x16x32_bf16 v[12:15], v[140:143], v[208:211], v[12:15]
	v_mfma_f32_16x16x32_bf16 v[64:67], v[136:139], v[188:191], v[64:67]
	v_mfma_f32_16x16x32_bf16 v[60:63], v[144:147], v[188:191], v[60:63]
	v_mfma_f32_16x16x32_bf16 v[48:51], v[136:139], v[196:199], v[48:51]
	v_mfma_f32_16x16x32_bf16 v[44:47], v[144:147], v[196:199], v[44:47]
	v_mfma_f32_16x16x32_bf16 v[32:35], v[136:139], v[204:207], v[32:35]
	v_mfma_f32_16x16x32_bf16 v[28:31], v[144:147], v[204:207], v[28:31]
	v_mfma_f32_16x16x32_bf16 v[16:19], v[136:139], v[212:215], v[16:19]
	v_mfma_f32_16x16x32_bf16 v[12:15], v[144:147], v[212:215], v[12:15]
	v_mfma_f32_16x16x32_bf16 v[56:59], v[148:151], v[184:187], v[56:59]
	v_mfma_f32_16x16x32_bf16 v[52:55], v[166:169], v[184:187], v[52:55]
	v_mfma_f32_16x16x32_bf16 v[40:43], v[148:151], v[192:195], v[40:43]
	v_mfma_f32_16x16x32_bf16 v[36:39], v[166:169], v[192:195], v[36:39]
	v_mfma_f32_16x16x32_bf16 v[24:27], v[148:151], v[200:203], v[24:27]
	v_mfma_f32_16x16x32_bf16 v[20:23], v[166:169], v[200:203], v[20:23]
	v_mfma_f32_16x16x32_bf16 v[8:11], v[148:151], v[208:211], v[8:11]
	v_mfma_f32_16x16x32_bf16 v[4:7], v[166:169], v[208:211], v[4:7]
	v_mfma_f32_16x16x32_bf16 v[56:59], v[152:155], v[188:191], v[56:59]
	v_mfma_f32_16x16x32_bf16 v[52:55], v[170:173], v[188:191], v[52:55]
	v_mfma_f32_16x16x32_bf16 v[40:43], v[152:155], v[196:199], v[40:43]
	v_mfma_f32_16x16x32_bf16 v[36:39], v[170:173], v[196:199], v[36:39]
	v_mfma_f32_16x16x32_bf16 v[24:27], v[152:155], v[204:207], v[24:27]
	v_mfma_f32_16x16x32_bf16 v[20:23], v[170:173], v[204:207], v[20:23]
	v_mfma_f32_16x16x32_bf16 v[8:11], v[152:155], v[212:215], v[8:11]
	v_mfma_f32_16x16x32_bf16 v[4:7], v[170:173], v[212:215], v[4:7]
	s_barrier

	s_add_i32 vcc_lo, vcc_lo, 2
	s_add_u32 s44, s44, 0x100
	s_addc_u32 s45, s45, 0
	s_add_u32 s91, s91, 0x100
	s_addc_u32 s96, s96, 0
	s_cmp_gt_u32 vcc_lo, 29
	s_cbranch_scc0 .LBB0_870
	s_setprio 0

.LBB0_1035:
	s_add_u32 s46, s50, 0x100
	s_addc_u32 s47, s51, 0
	s_add_i32 s16, 0, 0x10000
	s_cmpk_eq_i32 s48, 0x54
	s_cselect_b32 s73, s23, s47
	s_cselect_b32 s72, s22, s46
	s_cselect_b32 s29, s27, vcc_hi
	s_cselect_b32 s28, s26, vcc_lo
	s_add_i32 s49, 0, 0x14000
	ds_read_b128 v[132:135], v174
	ds_read_b128 v[136:139], v174 offset:1024
	ds_read_b128 v[140:143], v174 offset:2048
	ds_read_b128 v[144:147], v174 offset:3072
	ds_read_b128 v[148:151], v175
	ds_read_b128 v[152:155], v175 offset:1024
	ds_read_b128 v[156:159], v175 offset:2048
	ds_read_b128 v[160:163], v175 offset:3072
	s_add_i32 m0, s77, 0xc000
	ds_read_b128 v[164:167], v246
	ds_read_b128 v[188:191], v246 offset:1024
	ds_read_b128 v[192:195], v246 offset:2048
	ds_read_b128 v[196:199], v246 offset:3072
	ds_read_b128 v[200:203], v246 offset:4096
	ds_read_b128 v[204:207], v246 offset:5120
	ds_read_b128 v[208:211], v246 offset:6144
	ds_read_b128 v[212:215], v246 offset:7168
	global_load_lds_dwordx4 v184, s[50:51]
	s_add_i32 m0, s77, 0xe000
	s_nop 0
	global_load_lds_dwordx4 v186, s[50:51]
	s_waitcnt vmcnt(8)
	s_waitcnt lgkmcnt(0)

	s_barrier
	v_mfma_f32_16x16x32_bf16 v[128:131], v[132:135], v[164:167], v[128:131]
	v_mfma_f32_16x16x32_bf16 v[124:127], v[140:143], v[164:167], v[124:127]
	v_mfma_f32_16x16x32_bf16 v[112:115], v[132:135], v[192:195], v[112:115]
	v_mfma_f32_16x16x32_bf16 v[108:111], v[140:143], v[192:195], v[108:111]
	v_mfma_f32_16x16x32_bf16 v[96:99], v[132:135], v[200:203], v[96:99]
	v_mfma_f32_16x16x32_bf16 v[92:95], v[140:143], v[200:203], v[92:95]
	v_mfma_f32_16x16x32_bf16 v[80:83], v[132:135], v[208:211], v[80:83]
	v_mfma_f32_16x16x32_bf16 v[76:79], v[140:143], v[208:211], v[76:79]
	v_mfma_f32_16x16x32_bf16 v[128:131], v[136:139], v[188:191], v[128:131]
	v_mfma_f32_16x16x32_bf16 v[124:127], v[144:147], v[188:191], v[124:127]
	v_mfma_f32_16x16x32_bf16 v[112:115], v[136:139], v[196:199], v[112:115]
	v_mfma_f32_16x16x32_bf16 v[108:111], v[144:147], v[196:199], v[108:111]
	v_mfma_f32_16x16x32_bf16 v[96:99], v[136:139], v[204:207], v[96:99]
	v_mfma_f32_16x16x32_bf16 v[92:95], v[144:147], v[204:207], v[92:95]
	v_mfma_f32_16x16x32_bf16 v[80:83], v[136:139], v[212:215], v[80:83]
	v_mfma_f32_16x16x32_bf16 v[76:79], v[144:147], v[212:215], v[76:79]
	v_mfma_f32_16x16x32_bf16 v[120:123], v[148:151], v[164:167], v[120:123]
	v_mfma_f32_16x16x32_bf16 v[116:119], v[156:159], v[164:167], v[116:119]
	v_mfma_f32_16x16x32_bf16 v[104:107], v[148:151], v[192:195], v[104:107]
	v_mfma_f32_16x16x32_bf16 v[100:103], v[156:159], v[192:195], v[100:103]
	v_mfma_f32_16x16x32_bf16 v[88:91], v[148:151], v[200:203], v[88:91]
	v_mfma_f32_16x16x32_bf16 v[84:87], v[156:159], v[200:203], v[84:87]
	v_mfma_f32_16x16x32_bf16 v[72:75], v[148:151], v[208:211], v[72:75]
	v_mfma_f32_16x16x32_bf16 v[68:71], v[156:159], v[208:211], v[68:71]
	v_mfma_f32_16x16x32_bf16 v[120:123], v[152:155], v[188:191], v[120:123]
	v_mfma_f32_16x16x32_bf16 v[116:119], v[160:163], v[188:191], v[116:119]
	v_mfma_f32_16x16x32_bf16 v[104:107], v[152:155], v[196:199], v[104:107]
	v_mfma_f32_16x16x32_bf16 v[100:103], v[160:163], v[196:199], v[100:103]
	v_mfma_f32_16x16x32_bf16 v[88:91], v[152:155], v[204:207], v[88:91]
	v_mfma_f32_16x16x32_bf16 v[84:87], v[160:163], v[204:207], v[84:87]
	v_mfma_f32_16x16x32_bf16 v[72:75], v[152:155], v[212:215], v[72:75]
	v_mfma_f32_16x16x32_bf16 v[68:71], v[160:163], v[212:215], v[68:71]
	s_barrier

	s_add_i32 s16, s16, s74
	s_mov_b32 m0, s16
	ds_read_b128 v[164:167], v246 offset:16384
	ds_read_b128 v[188:191], v246 offset:17408
	ds_read_b128 v[192:195], v246 offset:18432
	ds_read_b128 v[196:199], v246 offset:19456
	ds_read_b128 v[200:203], v246 offset:20480
	ds_read_b128 v[204:207], v246 offset:21504
	ds_read_b128 v[208:211], v246 offset:22528
	ds_read_b128 v[212:215], v246 offset:23552
	global_load_lds_dwordx4 v2, s[28:29]
	s_add_i32 m0, s16, 0x2000
	s_add_u32 s16, s28, 0x58000
	s_addc_u32 s17, s29, 0
	s_add_i32 s49, s49, s74
	global_load_lds_dwordx4 v168, s[28:29]
	s_mov_b32 m0, s49
	s_nop 0
	global_load_lds_dwordx4 v2, s[16:17]
	s_add_i32 m0, s49, 0x2000
	s_nop 0
	global_load_lds_dwordx4 v168, s[16:17]
	s_mov_b32 m0, s77
	s_nop 0
	global_load_lds_dwordx4 v172, s[72:73]
	s_mov_b32 m0, s78
	s_nop 0
	global_load_lds_dwordx4 v170, s[72:73]
	s_waitcnt vmcnt(8)
	s_waitcnt lgkmcnt(0)

	s_barrier
	v_mfma_f32_16x16x32_bf16 v[64:67], v[132:135], v[164:167], v[64:67]
	v_mfma_f32_16x16x32_bf16 v[60:63], v[140:143], v[164:167], v[60:63]
	v_mfma_f32_16x16x32_bf16 v[48:51], v[132:135], v[192:195], v[48:51]
	v_mfma_f32_16x16x32_bf16 v[44:47], v[140:143], v[192:195], v[44:47]
	v_mfma_f32_16x16x32_bf16 v[32:35], v[132:135], v[200:203], v[32:35]
	v_mfma_f32_16x16x32_bf16 v[28:31], v[140:143], v[200:203], v[28:31]
	v_mfma_f32_16x16x32_bf16 v[16:19], v[132:135], v[208:211], v[16:19]
	v_mfma_f32_16x16x32_bf16 v[12:15], v[140:143], v[208:211], v[12:15]
	v_mfma_f32_16x16x32_bf16 v[64:67], v[136:139], v[188:191], v[64:67]
	v_mfma_f32_16x16x32_bf16 v[60:63], v[144:147], v[188:191], v[60:63]
	v_mfma_f32_16x16x32_bf16 v[48:51], v[136:139], v[196:199], v[48:51]
	v_mfma_f32_16x16x32_bf16 v[44:47], v[144:147], v[196:199], v[44:47]
	v_mfma_f32_16x16x32_bf16 v[32:35], v[136:139], v[204:207], v[32:35]
	v_mfma_f32_16x16x32_bf16 v[28:31], v[144:147], v[204:207], v[28:31]
	v_mfma_f32_16x16x32_bf16 v[16:19], v[136:139], v[212:215], v[16:19]
	v_mfma_f32_16x16x32_bf16 v[12:15], v[144:147], v[212:215], v[12:15]
	v_mfma_f32_16x16x32_bf16 v[56:59], v[148:151], v[164:167], v[56:59]
	v_mfma_f32_16x16x32_bf16 v[52:55], v[156:159], v[164:167], v[52:55]
	v_mfma_f32_16x16x32_bf16 v[40:43], v[148:151], v[192:195], v[40:43]
	v_mfma_f32_16x16x32_bf16 v[36:39], v[156:159], v[192:195], v[36:39]
	v_mfma_f32_16x16x32_bf16 v[24:27], v[148:151], v[200:203], v[24:27]
	v_mfma_f32_16x16x32_bf16 v[20:23], v[156:159], v[200:203], v[20:23]
	v_mfma_f32_16x16x32_bf16 v[8:11], v[148:151], v[208:211], v[8:11]
	v_mfma_f32_16x16x32_bf16 v[4:7], v[156:159], v[208:211], v[4:7]
	v_mfma_f32_16x16x32_bf16 v[56:59], v[152:155], v[188:191], v[56:59]
	v_mfma_f32_16x16x32_bf16 v[52:55], v[160:163], v[188:191], v[52:55]
	v_mfma_f32_16x16x32_bf16 v[40:43], v[152:155], v[196:199], v[40:43]
	v_mfma_f32_16x16x32_bf16 v[36:39], v[160:163], v[196:199], v[36:39]
	v_mfma_f32_16x16x32_bf16 v[24:27], v[152:155], v[204:207], v[24:27]
	v_mfma_f32_16x16x32_bf16 v[20:23], v[160:163], v[204:207], v[20:23]
	v_mfma_f32_16x16x32_bf16 v[8:11], v[152:155], v[212:215], v[8:11]
	v_mfma_f32_16x16x32_bf16 v[4:7], v[160:163], v[212:215], v[4:7]
	s_barrier

	s_add_i32 s49, 0, 0x18000
	s_add_i32 s50, 0, 0x1c000
	ds_read_b128 v[132:135], v176
	ds_read_b128 v[136:139], v176 offset:1024
	ds_read_b128 v[140:143], v176 offset:2048
	ds_read_b128 v[144:147], v176 offset:3072
	ds_read_b128 v[148:151], v177
	ds_read_b128 v[152:155], v177 offset:1024
	ds_read_b128 v[156:159], v177 offset:2048
	ds_read_b128 v[160:163], v177 offset:3072
	s_add_u32 s16, s72, 0x160000
	s_addc_u32 s17, s73, 0
	s_mov_b32 m0, s18
	ds_read_b128 v[164:167], v246 offset:32768
	ds_read_b128 v[188:191], v246 offset:33792
	ds_read_b128 v[192:195], v246 offset:34816
	ds_read_b128 v[196:199], v246 offset:35840
	ds_read_b128 v[200:203], v246 offset:36864
	ds_read_b128 v[204:207], v246 offset:37888
	ds_read_b128 v[208:211], v246 offset:38912
	ds_read_b128 v[212:215], v246 offset:39936
	global_load_lds_dwordx4 v172, s[16:17]
	s_mov_b32 m0, s19
	s_nop 0
	global_load_lds_dwordx4 v170, s[16:17]
	s_waitcnt vmcnt(8)
	s_waitcnt lgkmcnt(0)

	s_barrier
	v_mfma_f32_16x16x32_bf16 v[128:131], v[132:135], v[164:167], v[128:131]
	v_mfma_f32_16x16x32_bf16 v[124:127], v[140:143], v[164:167], v[124:127]
	v_mfma_f32_16x16x32_bf16 v[112:115], v[132:135], v[192:195], v[112:115]
	v_mfma_f32_16x16x32_bf16 v[108:111], v[140:143], v[192:195], v[108:111]
	v_mfma_f32_16x16x32_bf16 v[96:99], v[132:135], v[200:203], v[96:99]
	v_mfma_f32_16x16x32_bf16 v[92:95], v[140:143], v[200:203], v[92:95]
	v_mfma_f32_16x16x32_bf16 v[80:83], v[132:135], v[208:211], v[80:83]
	v_mfma_f32_16x16x32_bf16 v[76:79], v[140:143], v[208:211], v[76:79]
	v_mfma_f32_16x16x32_bf16 v[128:131], v[136:139], v[188:191], v[128:131]
	v_mfma_f32_16x16x32_bf16 v[124:127], v[144:147], v[188:191], v[124:127]
	v_mfma_f32_16x16x32_bf16 v[112:115], v[136:139], v[196:199], v[112:115]
	v_mfma_f32_16x16x32_bf16 v[108:111], v[144:147], v[196:199], v[108:111]
	v_mfma_f32_16x16x32_bf16 v[96:99], v[136:139], v[204:207], v[96:99]
	v_mfma_f32_16x16x32_bf16 v[92:95], v[144:147], v[204:207], v[92:95]
	v_mfma_f32_16x16x32_bf16 v[80:83], v[136:139], v[212:215], v[80:83]
	v_mfma_f32_16x16x32_bf16 v[76:79], v[144:147], v[212:215], v[76:79]
	v_mfma_f32_16x16x32_bf16 v[120:123], v[148:151], v[164:167], v[120:123]
	v_mfma_f32_16x16x32_bf16 v[116:119], v[156:159], v[164:167], v[116:119]
	v_mfma_f32_16x16x32_bf16 v[104:107], v[148:151], v[192:195], v[104:107]
	v_mfma_f32_16x16x32_bf16 v[100:103], v[156:159], v[192:195], v[100:103]
	v_mfma_f32_16x16x32_bf16 v[88:91], v[148:151], v[200:203], v[88:91]
	v_mfma_f32_16x16x32_bf16 v[84:87], v[156:159], v[200:203], v[84:87]
	v_mfma_f32_16x16x32_bf16 v[72:75], v[148:151], v[208:211], v[72:75]
	v_mfma_f32_16x16x32_bf16 v[68:71], v[156:159], v[208:211], v[68:71]
	v_mfma_f32_16x16x32_bf16 v[120:123], v[152:155], v[188:191], v[120:123]
	v_mfma_f32_16x16x32_bf16 v[116:119], v[160:163], v[188:191], v[116:119]
	v_mfma_f32_16x16x32_bf16 v[104:107], v[152:155], v[196:199], v[104:107]
	v_mfma_f32_16x16x32_bf16 v[100:103], v[160:163], v[196:199], v[100:103]
	v_mfma_f32_16x16x32_bf16 v[88:91], v[152:155], v[204:207], v[88:91]
	v_mfma_f32_16x16x32_bf16 v[84:87], v[160:163], v[204:207], v[84:87]
	v_mfma_f32_16x16x32_bf16 v[72:75], v[152:155], v[212:215], v[72:75]
	v_mfma_f32_16x16x32_bf16 v[68:71], v[160:163], v[212:215], v[68:71]
	s_barrier

	s_add_i32 s16, s49, s74
	s_mov_b32 m0, s16
	ds_read_b128 v[164:167], v246 offset:49152
	ds_read_b128 v[188:191], v246 offset:50176
	ds_read_b128 v[192:195], v246 offset:51200
	ds_read_b128 v[196:199], v246 offset:52224
	ds_read_b128 v[200:203], v246 offset:53248
	ds_read_b128 v[204:207], v246 offset:54272
	ds_read_b128 v[208:211], v246 offset:55296
	ds_read_b128 v[212:215], v246 offset:56320
	s_add_u32 s100, s28, s24
	s_addc_u32 s101, s29, s25
	global_load_lds_dwordx4 v2, s[100:101]
	s_add_i32 m0, s16, 0x2000
	s_add_u32 s16, s28, 0x58080
	s_addc_u32 s17, s29, 0
	s_add_i32 s28, s50, s74
	global_load_lds_dwordx4 v168, s[100:101]
	s_mov_b32 m0, s28
	s_nop 0
	global_load_lds_dwordx4 v2, s[16:17]
	s_add_i32 m0, s28, 0x2000
	s_nop 0
	global_load_lds_dwordx4 v168, s[16:17]
	s_mov_b32 m0, s96
	s_nop 0
	s_add_u32 s100, s72, s24
	s_addc_u32 s101, s73, s25
	global_load_lds_dwordx4 v172, s[100:101]
	s_mov_b32 m0, s3
	s_nop 0
	global_load_lds_dwordx4 v170, s[100:101]
	s_waitcnt vmcnt(8)
	s_waitcnt lgkmcnt(0)

	s_barrier
	v_mfma_f32_16x16x32_bf16 v[64:67], v[132:135], v[164:167], v[64:67]
	v_mfma_f32_16x16x32_bf16 v[60:63], v[140:143], v[164:167], v[60:63]
	v_mfma_f32_16x16x32_bf16 v[48:51], v[132:135], v[192:195], v[48:51]
	v_mfma_f32_16x16x32_bf16 v[44:47], v[140:143], v[192:195], v[44:47]
	v_mfma_f32_16x16x32_bf16 v[32:35], v[132:135], v[200:203], v[32:35]
	v_mfma_f32_16x16x32_bf16 v[28:31], v[140:143], v[200:203], v[28:31]
	v_mfma_f32_16x16x32_bf16 v[16:19], v[132:135], v[208:211], v[16:19]
	v_mfma_f32_16x16x32_bf16 v[12:15], v[140:143], v[208:211], v[12:15]
	v_mfma_f32_16x16x32_bf16 v[64:67], v[136:139], v[188:191], v[64:67]
	v_mfma_f32_16x16x32_bf16 v[60:63], v[144:147], v[188:191], v[60:63]
	v_mfma_f32_16x16x32_bf16 v[48:51], v[136:139], v[196:199], v[48:51]
	v_mfma_f32_16x16x32_bf16 v[44:47], v[144:147], v[196:199], v[44:47]
	v_mfma_f32_16x16x32_bf16 v[32:35], v[136:139], v[204:207], v[32:35]
	v_mfma_f32_16x16x32_bf16 v[28:31], v[144:147], v[204:207], v[28:31]
	v_mfma_f32_16x16x32_bf16 v[16:19], v[136:139], v[212:215], v[16:19]
	v_mfma_f32_16x16x32_bf16 v[12:15], v[144:147], v[212:215], v[12:15]
	v_mfma_f32_16x16x32_bf16 v[56:59], v[148:151], v[164:167], v[56:59]
	v_mfma_f32_16x16x32_bf16 v[52:55], v[156:159], v[164:167], v[52:55]
	v_mfma_f32_16x16x32_bf16 v[40:43], v[148:151], v[192:195], v[40:43]
	v_mfma_f32_16x16x32_bf16 v[36:39], v[156:159], v[192:195], v[36:39]
	v_mfma_f32_16x16x32_bf16 v[24:27], v[148:151], v[200:203], v[24:27]
	v_mfma_f32_16x16x32_bf16 v[20:23], v[156:159], v[200:203], v[20:23]
	v_mfma_f32_16x16x32_bf16 v[8:11], v[148:151], v[208:211], v[8:11]
	v_mfma_f32_16x16x32_bf16 v[4:7], v[156:159], v[208:211], v[4:7]
	v_mfma_f32_16x16x32_bf16 v[56:59], v[152:155], v[188:191], v[56:59]
	v_mfma_f32_16x16x32_bf16 v[52:55], v[160:163], v[188:191], v[52:55]
	v_mfma_f32_16x16x32_bf16 v[40:43], v[152:155], v[196:199], v[40:43]
	v_mfma_f32_16x16x32_bf16 v[36:39], v[160:163], v[196:199], v[36:39]
	v_mfma_f32_16x16x32_bf16 v[24:27], v[152:155], v[204:207], v[24:27]
	v_mfma_f32_16x16x32_bf16 v[20:23], v[160:163], v[204:207], v[20:23]
	v_mfma_f32_16x16x32_bf16 v[8:11], v[152:155], v[212:215], v[8:11]
	v_mfma_f32_16x16x32_bf16 v[4:7], v[160:163], v[212:215], v[4:7]
	s_barrier

	s_add_i32 s48, s48, 2
	s_add_u32 vcc_lo, vcc_lo, 0x100
	s_addc_u32 vcc_hi, vcc_hi, 0
	s_cmpk_gt_u32 s48, 0x55
	s_mov_b64 s[50:51], s[46:47]
	s_cbranch_scc0 .LBB0_1035
	s_setprio 0
	v_readlane_b32 s16, v252, 12
	v_readlane_b32 s17, v252, 13
